# GEMM K-loops: the s_waitcnt lgkmcnt(0) repeated right after each section barrier removed (the same wait already sits before the barrier)
# speedup vs baseline: 1.0008x; 1.0008x over previous
.LBB0_157:
	ds_read_b128 v[154:157], v151
	ds_read_b128 v[158:161], v151 offset:1024
	ds_read_b128 v[162:165], v151 offset:2048
	ds_read_b128 v[166:169], v151 offset:3072
	ds_read_b128 v[170:173], v152
	ds_read_b128 v[174:177], v152 offset:1024
	ds_read_b128 v[178:181], v152 offset:2048
	ds_read_b128 v[182:185], v152 offset:3072
	s_add_u32 s8, s26, 0xfffc0080
	s_addc_u32 s9, s27, -1
	s_cmp_eq_u32 s45, 12
	s_cselect_b32 s29, s13, s9
	s_cselect_b32 s28, s39, s8
	s_cselect_b32 s9, s11, s44
	s_cselect_b32 s8, s40, s41
	v_lshl_add_u64 v[144:145], s[26:27], 0, v[136:137]
	s_add_i32 m0, s16, 0xc000
	ds_read_b128 v[186:189], v153
	ds_read_b128 v[190:193], v153 offset:1024
	ds_read_b128 v[196:199], v153 offset:2048
	ds_read_b128 v[200:203], v153 offset:3072
	ds_read_b128 v[204:207], v153 offset:4096
	ds_read_b128 v[208:211], v153 offset:5120
	ds_read_b128 v[212:215], v153 offset:6144
	ds_read_b128 v[216:219], v153 offset:7168
	global_load_lds_dwordx4 v[144:145], off
	v_lshl_add_u64 v[144:145], s[26:27], 0, v[138:139]
	s_add_i32 m0, s16, 0xe000
	s_nop 0
	global_load_lds_dwordx4 v[144:145], off
	s_waitcnt vmcnt(8)
	s_waitcnt lgkmcnt(0)
	s_barrier
	s_setprio 1
	v_mfma_f32_16x16x32_bf16 v[124:127], v[154:157], v[186:189], v[124:127]
	v_mfma_f32_16x16x32_bf16 v[120:123], v[162:165], v[186:189], v[120:123]
	v_mfma_f32_16x16x32_bf16 v[116:119], v[154:157], v[196:199], v[116:119]
	v_mfma_f32_16x16x32_bf16 v[108:111], v[162:165], v[196:199], v[108:111]
	v_mfma_f32_16x16x32_bf16 v[96:99], v[154:157], v[204:207], v[96:99]
	v_mfma_f32_16x16x32_bf16 v[88:91], v[162:165], v[204:207], v[88:91]
	v_mfma_f32_16x16x32_bf16 v[84:87], v[154:157], v[212:215], v[84:87]
	v_mfma_f32_16x16x32_bf16 v[76:79], v[162:165], v[212:215], v[76:79]
	v_mfma_f32_16x16x32_bf16 v[124:127], v[158:161], v[190:193], v[124:127]
	v_mfma_f32_16x16x32_bf16 v[120:123], v[166:169], v[190:193], v[120:123]
	v_mfma_f32_16x16x32_bf16 v[116:119], v[158:161], v[200:203], v[116:119]
	v_mfma_f32_16x16x32_bf16 v[108:111], v[166:169], v[200:203], v[108:111]
	v_mfma_f32_16x16x32_bf16 v[96:99], v[158:161], v[208:211], v[96:99]
	v_mfma_f32_16x16x32_bf16 v[88:91], v[166:169], v[208:211], v[88:91]
	v_mfma_f32_16x16x32_bf16 v[84:87], v[158:161], v[216:219], v[84:87]
	v_mfma_f32_16x16x32_bf16 v[76:79], v[166:169], v[216:219], v[76:79]
	s_setprio 0
	s_setprio 1
	v_mfma_f32_16x16x32_bf16 v[112:115], v[170:173], v[186:189], v[112:115]
	v_mfma_f32_16x16x32_bf16 v[104:107], v[178:181], v[186:189], v[104:107]
	v_mfma_f32_16x16x32_bf16 v[100:103], v[170:173], v[196:199], v[100:103]
	v_mfma_f32_16x16x32_bf16 v[92:95], v[178:181], v[196:199], v[92:95]
	v_mfma_f32_16x16x32_bf16 v[80:83], v[170:173], v[204:207], v[80:83]
	v_mfma_f32_16x16x32_bf16 v[72:75], v[178:181], v[204:207], v[72:75]
	v_mfma_f32_16x16x32_bf16 v[68:71], v[170:173], v[212:215], v[68:71]
	v_mfma_f32_16x16x32_bf16 v[64:67], v[178:181], v[212:215], v[64:67]
	v_mfma_f32_16x16x32_bf16 v[112:115], v[174:177], v[190:193], v[112:115]
	v_mfma_f32_16x16x32_bf16 v[104:107], v[182:185], v[190:193], v[104:107]
	v_mfma_f32_16x16x32_bf16 v[100:103], v[174:177], v[200:203], v[100:103]
	v_mfma_f32_16x16x32_bf16 v[92:95], v[182:185], v[200:203], v[92:95]
	v_mfma_f32_16x16x32_bf16 v[80:83], v[174:177], v[208:211], v[80:83]
	v_mfma_f32_16x16x32_bf16 v[72:75], v[182:185], v[208:211], v[72:75]
	v_mfma_f32_16x16x32_bf16 v[68:71], v[174:177], v[216:219], v[68:71]
	v_mfma_f32_16x16x32_bf16 v[64:67], v[182:185], v[216:219], v[64:67]
	s_setprio 0
	s_barrier
	s_add_i32 s46, s31, s3
	v_lshl_add_u64 v[144:145], s[8:9], 0, v[132:133]
	s_mov_b32 m0, s46
	ds_read_b128 v[186:189], v153 offset:16384
	ds_read_b128 v[190:193], v153 offset:17408
	ds_read_b128 v[196:199], v153 offset:18432
	ds_read_b128 v[200:203], v153 offset:19456
	ds_read_b128 v[204:207], v153 offset:20480
	ds_read_b128 v[208:211], v153 offset:21504
	ds_read_b128 v[212:215], v153 offset:22528
	ds_read_b128 v[216:219], v153 offset:23552
	global_load_lds_dwordx4 v[144:145], off
	s_add_i32 m0, s46, 0x2000
	s_add_u32 s46, s8, 0x40000
	v_lshl_add_u64 v[220:221], s[8:9], 0, v[128:129]
	s_addc_u32 s47, s9, 0
	s_add_i32 s48, s33, s3
	global_load_lds_dwordx4 v[220:221], off
	v_lshl_add_u64 v[222:223], s[46:47], 0, v[132:133]
	s_mov_b32 m0, s48
	v_lshl_add_u64 v[224:225], s[28:29], 0, v[130:131]
	global_load_lds_dwordx4 v[222:223], off
	v_lshl_add_u64 v[222:223], s[46:47], 0, v[128:129]
	s_add_i32 m0, s48, 0x2000
	s_nop 0
	global_load_lds_dwordx4 v[222:223], off
	v_lshl_add_u64 v[222:223], s[28:29], 0, v[134:135]
	s_mov_b32 m0, s16
	s_nop 0
	global_load_lds_dwordx4 v[222:223], off
	s_mov_b32 m0, s17
	s_nop 0
	global_load_lds_dwordx4 v[224:225], off
	s_waitcnt vmcnt(8)
	s_waitcnt lgkmcnt(0)
	s_barrier
	s_setprio 1
	v_mfma_f32_16x16x32_bf16 v[60:63], v[154:157], v[186:189], v[60:63]
	v_mfma_f32_16x16x32_bf16 v[56:59], v[162:165], v[186:189], v[56:59]
	v_mfma_f32_16x16x32_bf16 v[52:55], v[154:157], v[196:199], v[52:55]
	v_mfma_f32_16x16x32_bf16 v[44:47], v[162:165], v[196:199], v[44:47]
	v_mfma_f32_16x16x32_bf16 v[32:35], v[154:157], v[204:207], v[32:35]
	v_mfma_f32_16x16x32_bf16 v[24:27], v[162:165], v[204:207], v[24:27]
	v_mfma_f32_16x16x32_bf16 v[20:23], v[154:157], v[212:215], v[20:23]
	v_mfma_f32_16x16x32_bf16 v[12:15], v[162:165], v[212:215], v[12:15]
	v_mfma_f32_16x16x32_bf16 v[60:63], v[158:161], v[190:193], v[60:63]
	v_mfma_f32_16x16x32_bf16 v[56:59], v[166:169], v[190:193], v[56:59]
	v_mfma_f32_16x16x32_bf16 v[52:55], v[158:161], v[200:203], v[52:55]
	v_mfma_f32_16x16x32_bf16 v[44:47], v[166:169], v[200:203], v[44:47]
	v_mfma_f32_16x16x32_bf16 v[32:35], v[158:161], v[208:211], v[32:35]
	v_mfma_f32_16x16x32_bf16 v[24:27], v[166:169], v[208:211], v[24:27]
	v_mfma_f32_16x16x32_bf16 v[20:23], v[158:161], v[216:219], v[20:23]
	v_mfma_f32_16x16x32_bf16 v[12:15], v[166:169], v[216:219], v[12:15]
	s_setprio 0
	s_setprio 1
	v_mfma_f32_16x16x32_bf16 v[48:51], v[170:173], v[186:189], v[48:51]
	v_mfma_f32_16x16x32_bf16 v[40:43], v[178:181], v[186:189], v[40:43]
	v_mfma_f32_16x16x32_bf16 v[36:39], v[170:173], v[196:199], v[36:39]
	v_mfma_f32_16x16x32_bf16 v[28:31], v[178:181], v[196:199], v[28:31]
	v_mfma_f32_16x16x32_bf16 v[16:19], v[170:173], v[204:207], v[16:19]
	v_mfma_f32_16x16x32_bf16 v[8:11], v[178:181], v[204:207], v[8:11]
	v_mfma_f32_16x16x32_bf16 v[4:7], v[170:173], v[212:215], v[4:7]
	v_mfma_f32_16x16x32_bf16 v[0:3], v[178:181], v[212:215], v[0:3]
	v_mfma_f32_16x16x32_bf16 v[48:51], v[174:177], v[190:193], v[48:51]
	v_mfma_f32_16x16x32_bf16 v[40:43], v[182:185], v[190:193], v[40:43]
	v_mfma_f32_16x16x32_bf16 v[36:39], v[174:177], v[200:203], v[36:39]
	v_mfma_f32_16x16x32_bf16 v[28:31], v[182:185], v[200:203], v[28:31]
	v_mfma_f32_16x16x32_bf16 v[16:19], v[174:177], v[208:211], v[16:19]
	v_mfma_f32_16x16x32_bf16 v[8:11], v[182:185], v[208:211], v[8:11]
	v_mfma_f32_16x16x32_bf16 v[4:7], v[174:177], v[216:219], v[4:7]
	v_mfma_f32_16x16x32_bf16 v[0:3], v[182:185], v[216:219], v[0:3]
	s_setprio 0
	s_barrier
	s_add_i32 s46, 0, 0x18000
	s_add_i32 s47, 0, 0x1c000
	v_add_u32_e32 v166, s46, v148
	v_add_u32_e32 v182, s47, v148
	ds_read_b128 v[154:157], v166
	ds_read_b128 v[158:161], v166 offset:1024
	ds_read_b128 v[162:165], v166 offset:2048
	ds_read_b128 v[166:169], v166 offset:3072
	ds_read_b128 v[170:173], v182
	ds_read_b128 v[174:177], v182 offset:1024
	ds_read_b128 v[178:181], v182 offset:2048
	ds_read_b128 v[182:185], v182 offset:3072
	s_add_u32 s28, s28, 0x40000
	s_addc_u32 s29, s29, 0
	s_mov_b32 m0, s18
	v_lshl_add_u64 v[226:227], s[28:29], 0, v[134:135]
	ds_read_b128 v[186:189], v153 offset:32768
	ds_read_b128 v[190:193], v153 offset:33792
	ds_read_b128 v[196:199], v153 offset:34816
	ds_read_b128 v[200:203], v153 offset:35840
	ds_read_b128 v[204:207], v153 offset:36864
	ds_read_b128 v[208:211], v153 offset:37888
	ds_read_b128 v[212:215], v153 offset:38912
	ds_read_b128 v[216:219], v153 offset:39936
	global_load_lds_dwordx4 v[226:227], off
	v_lshl_add_u64 v[226:227], s[28:29], 0, v[130:131]
	s_mov_b32 m0, s19
	s_nop 0
	global_load_lds_dwordx4 v[226:227], off
	s_waitcnt vmcnt(8)
	s_waitcnt lgkmcnt(0)
	s_barrier
	s_setprio 1
	v_mfma_f32_16x16x32_bf16 v[124:127], v[154:157], v[186:189], v[124:127]
	v_mfma_f32_16x16x32_bf16 v[120:123], v[162:165], v[186:189], v[120:123]
	v_mfma_f32_16x16x32_bf16 v[116:119], v[154:157], v[196:199], v[116:119]
	v_mfma_f32_16x16x32_bf16 v[108:111], v[162:165], v[196:199], v[108:111]
	v_mfma_f32_16x16x32_bf16 v[96:99], v[154:157], v[204:207], v[96:99]
	v_mfma_f32_16x16x32_bf16 v[88:91], v[162:165], v[204:207], v[88:91]
	v_mfma_f32_16x16x32_bf16 v[84:87], v[154:157], v[212:215], v[84:87]
	v_mfma_f32_16x16x32_bf16 v[76:79], v[162:165], v[212:215], v[76:79]
	v_mfma_f32_16x16x32_bf16 v[124:127], v[158:161], v[190:193], v[124:127]
	v_mfma_f32_16x16x32_bf16 v[120:123], v[166:169], v[190:193], v[120:123]
	v_mfma_f32_16x16x32_bf16 v[116:119], v[158:161], v[200:203], v[116:119]
	v_mfma_f32_16x16x32_bf16 v[108:111], v[166:169], v[200:203], v[108:111]
	v_mfma_f32_16x16x32_bf16 v[96:99], v[158:161], v[208:211], v[96:99]
	v_mfma_f32_16x16x32_bf16 v[88:91], v[166:169], v[208:211], v[88:91]
	v_mfma_f32_16x16x32_bf16 v[84:87], v[158:161], v[216:219], v[84:87]
	v_mfma_f32_16x16x32_bf16 v[76:79], v[166:169], v[216:219], v[76:79]
	s_setprio 0
	s_setprio 1
	v_mfma_f32_16x16x32_bf16 v[112:115], v[170:173], v[186:189], v[112:115]
	v_mfma_f32_16x16x32_bf16 v[104:107], v[178:181], v[186:189], v[104:107]
	v_mfma_f32_16x16x32_bf16 v[100:103], v[170:173], v[196:199], v[100:103]
	v_mfma_f32_16x16x32_bf16 v[92:95], v[178:181], v[196:199], v[92:95]
	v_mfma_f32_16x16x32_bf16 v[80:83], v[170:173], v[204:207], v[80:83]
	v_mfma_f32_16x16x32_bf16 v[72:75], v[178:181], v[204:207], v[72:75]
	v_mfma_f32_16x16x32_bf16 v[68:71], v[170:173], v[212:215], v[68:71]
	v_mfma_f32_16x16x32_bf16 v[64:67], v[178:181], v[212:215], v[64:67]
	v_mfma_f32_16x16x32_bf16 v[112:115], v[174:177], v[190:193], v[112:115]
	v_mfma_f32_16x16x32_bf16 v[104:107], v[182:185], v[190:193], v[104:107]
	v_mfma_f32_16x16x32_bf16 v[100:103], v[174:177], v[200:203], v[100:103]
	v_mfma_f32_16x16x32_bf16 v[92:95], v[182:185], v[200:203], v[92:95]
	v_mfma_f32_16x16x32_bf16 v[80:83], v[174:177], v[208:211], v[80:83]
	v_mfma_f32_16x16x32_bf16 v[72:75], v[182:185], v[208:211], v[72:75]
	v_mfma_f32_16x16x32_bf16 v[68:71], v[174:177], v[216:219], v[68:71]
	v_mfma_f32_16x16x32_bf16 v[64:67], v[182:185], v[216:219], v[64:67]
	s_setprio 0
	s_barrier
	s_add_i32 s28, s46, s3
	v_lshl_add_u64 v[144:145], v[144:145], 0, s[4:5]
	s_mov_b32 m0, s28
	ds_read_b128 v[186:189], v153 offset:49152
	ds_read_b128 v[190:193], v153 offset:50176
	ds_read_b128 v[196:199], v153 offset:51200
	ds_read_b128 v[200:203], v153 offset:52224
	ds_read_b128 v[204:207], v153 offset:53248
	ds_read_b128 v[208:211], v153 offset:54272
	ds_read_b128 v[212:215], v153 offset:55296
	ds_read_b128 v[216:219], v153 offset:56320
	global_load_lds_dwordx4 v[144:145], off
	s_add_i32 m0, s28, 0x2000
	s_add_u32 s8, s8, 0x40080
	v_lshl_add_u64 v[144:145], v[220:221], 0, s[4:5]
	s_addc_u32 s9, s9, 0
	s_add_i32 s28, s47, s3
	global_load_lds_dwordx4 v[144:145], off
	v_lshl_add_u64 v[144:145], s[8:9], 0, v[132:133]
	s_mov_b32 m0, s28
	s_nop 0
	global_load_lds_dwordx4 v[144:145], off
	v_lshl_add_u64 v[144:145], s[8:9], 0, v[128:129]
	s_add_i32 m0, s28, 0x2000
	s_nop 0
	global_load_lds_dwordx4 v[144:145], off
	v_lshl_add_u64 v[144:145], v[222:223], 0, s[4:5]
	s_mov_b32 m0, s25
	s_nop 0
	global_load_lds_dwordx4 v[144:145], off
	v_lshl_add_u64 v[144:145], v[224:225], 0, s[4:5]
	s_mov_b32 m0, s30
	s_nop 0
	global_load_lds_dwordx4 v[144:145], off
	s_waitcnt vmcnt(8)
	s_waitcnt lgkmcnt(0)
	s_barrier
	s_setprio 1
	v_mfma_f32_16x16x32_bf16 v[60:63], v[154:157], v[186:189], v[60:63]
	v_mfma_f32_16x16x32_bf16 v[56:59], v[162:165], v[186:189], v[56:59]
	v_mfma_f32_16x16x32_bf16 v[52:55], v[154:157], v[196:199], v[52:55]
	v_mfma_f32_16x16x32_bf16 v[44:47], v[162:165], v[196:199], v[44:47]
	v_mfma_f32_16x16x32_bf16 v[32:35], v[154:157], v[204:207], v[32:35]
	v_mfma_f32_16x16x32_bf16 v[24:27], v[162:165], v[204:207], v[24:27]
	v_mfma_f32_16x16x32_bf16 v[20:23], v[154:157], v[212:215], v[20:23]
	v_mfma_f32_16x16x32_bf16 v[12:15], v[162:165], v[212:215], v[12:15]
	v_mfma_f32_16x16x32_bf16 v[60:63], v[158:161], v[190:193], v[60:63]
	v_mfma_f32_16x16x32_bf16 v[56:59], v[166:169], v[190:193], v[56:59]
	v_mfma_f32_16x16x32_bf16 v[52:55], v[158:161], v[200:203], v[52:55]
	v_mfma_f32_16x16x32_bf16 v[44:47], v[166:169], v[200:203], v[44:47]
	v_mfma_f32_16x16x32_bf16 v[32:35], v[158:161], v[208:211], v[32:35]
	v_mfma_f32_16x16x32_bf16 v[24:27], v[166:169], v[208:211], v[24:27]
	v_mfma_f32_16x16x32_bf16 v[20:23], v[158:161], v[216:219], v[20:23]
	v_mfma_f32_16x16x32_bf16 v[12:15], v[166:169], v[216:219], v[12:15]
	s_setprio 0
	s_setprio 1
	v_mfma_f32_16x16x32_bf16 v[48:51], v[170:173], v[186:189], v[48:51]
	v_mfma_f32_16x16x32_bf16 v[40:43], v[178:181], v[186:189], v[40:43]
	v_mfma_f32_16x16x32_bf16 v[36:39], v[170:173], v[196:199], v[36:39]
	v_mfma_f32_16x16x32_bf16 v[28:31], v[178:181], v[196:199], v[28:31]
	v_mfma_f32_16x16x32_bf16 v[16:19], v[170:173], v[204:207], v[16:19]
	v_mfma_f32_16x16x32_bf16 v[8:11], v[178:181], v[204:207], v[8:11]
	v_mfma_f32_16x16x32_bf16 v[4:7], v[170:173], v[212:215], v[4:7]
	v_mfma_f32_16x16x32_bf16 v[0:3], v[178:181], v[212:215], v[0:3]
	v_mfma_f32_16x16x32_bf16 v[48:51], v[174:177], v[190:193], v[48:51]
	v_mfma_f32_16x16x32_bf16 v[40:43], v[182:185], v[190:193], v[40:43]
	v_mfma_f32_16x16x32_bf16 v[36:39], v[174:177], v[200:203], v[36:39]
	v_mfma_f32_16x16x32_bf16 v[28:31], v[182:185], v[200:203], v[28:31]
	v_mfma_f32_16x16x32_bf16 v[16:19], v[174:177], v[208:211], v[16:19]
	v_mfma_f32_16x16x32_bf16 v[8:11], v[182:185], v[208:211], v[8:11]
	v_mfma_f32_16x16x32_bf16 v[4:7], v[174:177], v[216:219], v[4:7]
	v_mfma_f32_16x16x32_bf16 v[0:3], v[182:185], v[216:219], v[0:3]
	s_setprio 0
	s_barrier
	s_add_i32 s45, s45, 2
	s_add_u32 s26, s26, 0x100
	s_addc_u32 s27, s27, 0
	s_add_u32 s41, s41, 0x100
	s_addc_u32 s44, s44, 0
	s_cmp_gt_u32 s45, 13
	s_cbranch_scc0 .LBB0_157
	s_and_b64 vcc, exec, s[6:7]
	s_cbranch_vccz .LBB0_160
	s_barrier

.LBB0_666:
	ds_read_b128 v[144:147], v153
	ds_read_b128 v[162:165], v153 offset:1024
	ds_read_b128 v[166:169], v153 offset:2048
	ds_read_b128 v[170:173], v153 offset:3072
	ds_read_b128 v[174:177], v154
	ds_read_b128 v[178:181], v154 offset:1024
	ds_read_b128 v[182:185], v154 offset:2048
	ds_read_b128 v[186:189], v154 offset:3072
	s_add_u32 s8, s38, 0xfffc0080
	s_addc_u32 s9, s39, -1
	s_cmp_eq_u32 s65, 12
	s_cselect_b32 s41, s27, s9
	s_cselect_b32 s40, s37, s8
	s_cselect_b32 s9, s25, s64
	s_cselect_b32 s8, s60, s61
	v_lshl_add_u64 v[156:157], s[38:39], 0, v[136:137]
	s_add_i32 m0, s4, 0xc000
	ds_read_b128 v[190:193], v155
	ds_read_b128 v[198:201], v155 offset:1024
	ds_read_b128 v[202:205], v155 offset:2048
	ds_read_b128 v[206:209], v155 offset:3072
	ds_read_b128 v[210:213], v155 offset:4096
	ds_read_b128 v[214:217], v155 offset:5120
	ds_read_b128 v[218:221], v155 offset:6144
	ds_read_b128 v[222:225], v155 offset:7168
	global_load_lds_dwordx4 v[156:157], off
	v_lshl_add_u64 v[156:157], s[38:39], 0, v[138:139]
	s_add_i32 m0, s4, 0xe000
	s_nop 0
	global_load_lds_dwordx4 v[156:157], off
	s_waitcnt vmcnt(8)
	s_waitcnt lgkmcnt(0)
	s_barrier
	s_setprio 1
	v_mfma_f32_16x16x32_bf16 v[124:127], v[144:147], v[190:193], v[124:127]
	v_mfma_f32_16x16x32_bf16 v[120:123], v[166:169], v[190:193], v[120:123]
	v_mfma_f32_16x16x32_bf16 v[108:111], v[144:147], v[202:205], v[108:111]
	v_mfma_f32_16x16x32_bf16 v[104:107], v[166:169], v[202:205], v[104:107]
	v_mfma_f32_16x16x32_bf16 v[92:95], v[144:147], v[210:213], v[92:95]
	v_mfma_f32_16x16x32_bf16 v[88:91], v[166:169], v[210:213], v[88:91]
	v_mfma_f32_16x16x32_bf16 v[76:79], v[144:147], v[218:221], v[76:79]
	v_mfma_f32_16x16x32_bf16 v[72:75], v[166:169], v[218:221], v[72:75]
	v_mfma_f32_16x16x32_bf16 v[124:127], v[162:165], v[198:201], v[124:127]
	v_mfma_f32_16x16x32_bf16 v[120:123], v[170:173], v[198:201], v[120:123]
	v_mfma_f32_16x16x32_bf16 v[108:111], v[162:165], v[206:209], v[108:111]
	v_mfma_f32_16x16x32_bf16 v[104:107], v[170:173], v[206:209], v[104:107]
	v_mfma_f32_16x16x32_bf16 v[92:95], v[162:165], v[214:217], v[92:95]
	v_mfma_f32_16x16x32_bf16 v[88:91], v[170:173], v[214:217], v[88:91]
	v_mfma_f32_16x16x32_bf16 v[76:79], v[162:165], v[222:225], v[76:79]
	v_mfma_f32_16x16x32_bf16 v[72:75], v[170:173], v[222:225], v[72:75]
	s_setprio 0
	s_setprio 1
	v_mfma_f32_16x16x32_bf16 v[116:119], v[174:177], v[190:193], v[116:119]
	v_mfma_f32_16x16x32_bf16 v[112:115], v[182:185], v[190:193], v[112:115]
	v_mfma_f32_16x16x32_bf16 v[100:103], v[174:177], v[202:205], v[100:103]
	v_mfma_f32_16x16x32_bf16 v[96:99], v[182:185], v[202:205], v[96:99]
	v_mfma_f32_16x16x32_bf16 v[84:87], v[174:177], v[210:213], v[84:87]
	v_mfma_f32_16x16x32_bf16 v[80:83], v[182:185], v[210:213], v[80:83]
	v_mfma_f32_16x16x32_bf16 v[68:71], v[174:177], v[218:221], v[68:71]
	v_mfma_f32_16x16x32_bf16 v[64:67], v[182:185], v[218:221], v[64:67]
	v_mfma_f32_16x16x32_bf16 v[116:119], v[178:181], v[198:201], v[116:119]
	v_mfma_f32_16x16x32_bf16 v[112:115], v[186:189], v[198:201], v[112:115]
	v_mfma_f32_16x16x32_bf16 v[100:103], v[178:181], v[206:209], v[100:103]
	v_mfma_f32_16x16x32_bf16 v[96:99], v[186:189], v[206:209], v[96:99]
	v_mfma_f32_16x16x32_bf16 v[84:87], v[178:181], v[214:217], v[84:87]
	v_mfma_f32_16x16x32_bf16 v[80:83], v[186:189], v[214:217], v[80:83]
	v_mfma_f32_16x16x32_bf16 v[68:71], v[178:181], v[222:225], v[68:71]
	v_mfma_f32_16x16x32_bf16 v[64:67], v[186:189], v[222:225], v[64:67]
	s_setprio 0
	s_barrier
	s_add_i32 s66, s55, s3
	v_lshl_add_u64 v[156:157], s[8:9], 0, v[130:131]
	s_mov_b32 m0, s66
	ds_read_b128 v[190:193], v155 offset:16384
	ds_read_b128 v[198:201], v155 offset:17408
	ds_read_b128 v[202:205], v155 offset:18432
	ds_read_b128 v[206:209], v155 offset:19456
	ds_read_b128 v[210:213], v155 offset:20480
	ds_read_b128 v[214:217], v155 offset:21504
	ds_read_b128 v[218:221], v155 offset:22528
	ds_read_b128 v[222:225], v155 offset:23552
	global_load_lds_dwordx4 v[156:157], off
	s_add_i32 m0, s66, 0x2000
	s_add_u32 s66, s8, 0x40000
	v_lshl_add_u64 v[226:227], s[8:9], 0, v[134:135]
	s_addc_u32 s67, s9, 0
	s_add_i32 s73, s58, s3
	global_load_lds_dwordx4 v[226:227], off
	v_lshl_add_u64 v[228:229], s[66:67], 0, v[130:131]
	s_mov_b32 m0, s73
	v_lshl_add_u64 v[230:231], s[40:41], 0, v[132:133]
	global_load_lds_dwordx4 v[228:229], off
	v_lshl_add_u64 v[228:229], s[66:67], 0, v[134:135]
	s_add_i32 m0, s73, 0x2000
	s_nop 0
	global_load_lds_dwordx4 v[228:229], off
	v_lshl_add_u64 v[228:229], s[40:41], 0, v[128:129]
	s_mov_b32 m0, s4
	s_nop 0
	global_load_lds_dwordx4 v[228:229], off
	s_mov_b32 m0, s5
	s_nop 0
	global_load_lds_dwordx4 v[230:231], off
	s_waitcnt vmcnt(8)
	s_waitcnt lgkmcnt(0)
	s_barrier
	s_setprio 1
	v_mfma_f32_16x16x32_bf16 v[60:63], v[144:147], v[190:193], v[60:63]
	v_mfma_f32_16x16x32_bf16 v[56:59], v[166:169], v[190:193], v[56:59]
	v_mfma_f32_16x16x32_bf16 v[44:47], v[144:147], v[202:205], v[44:47]
	v_mfma_f32_16x16x32_bf16 v[40:43], v[166:169], v[202:205], v[40:43]
	v_mfma_f32_16x16x32_bf16 v[28:31], v[144:147], v[210:213], v[28:31]
	v_mfma_f32_16x16x32_bf16 v[24:27], v[166:169], v[210:213], v[24:27]
	v_mfma_f32_16x16x32_bf16 v[12:15], v[144:147], v[218:221], v[12:15]
	v_mfma_f32_16x16x32_bf16 v[8:11], v[166:169], v[218:221], v[8:11]
	v_mfma_f32_16x16x32_bf16 v[60:63], v[162:165], v[198:201], v[60:63]
	v_mfma_f32_16x16x32_bf16 v[56:59], v[170:173], v[198:201], v[56:59]
	v_mfma_f32_16x16x32_bf16 v[44:47], v[162:165], v[206:209], v[44:47]
	v_mfma_f32_16x16x32_bf16 v[40:43], v[170:173], v[206:209], v[40:43]
	v_mfma_f32_16x16x32_bf16 v[28:31], v[162:165], v[214:217], v[28:31]
	v_mfma_f32_16x16x32_bf16 v[24:27], v[170:173], v[214:217], v[24:27]
	v_mfma_f32_16x16x32_bf16 v[12:15], v[162:165], v[222:225], v[12:15]
	v_mfma_f32_16x16x32_bf16 v[8:11], v[170:173], v[222:225], v[8:11]
	s_setprio 0
	s_setprio 1
	v_mfma_f32_16x16x32_bf16 v[52:55], v[174:177], v[190:193], v[52:55]
	v_mfma_f32_16x16x32_bf16 v[48:51], v[182:185], v[190:193], v[48:51]
	v_mfma_f32_16x16x32_bf16 v[36:39], v[174:177], v[202:205], v[36:39]
	v_mfma_f32_16x16x32_bf16 v[32:35], v[182:185], v[202:205], v[32:35]
	v_mfma_f32_16x16x32_bf16 v[20:23], v[174:177], v[210:213], v[20:23]
	v_mfma_f32_16x16x32_bf16 v[16:19], v[182:185], v[210:213], v[16:19]
	v_mfma_f32_16x16x32_bf16 v[4:7], v[174:177], v[218:221], v[4:7]
	v_mfma_f32_16x16x32_bf16 v[0:3], v[182:185], v[218:221], v[0:3]
	v_mfma_f32_16x16x32_bf16 v[52:55], v[178:181], v[198:201], v[52:55]
	v_mfma_f32_16x16x32_bf16 v[48:51], v[186:189], v[198:201], v[48:51]
	v_mfma_f32_16x16x32_bf16 v[36:39], v[178:181], v[206:209], v[36:39]
	v_mfma_f32_16x16x32_bf16 v[32:35], v[186:189], v[206:209], v[32:35]
	v_mfma_f32_16x16x32_bf16 v[20:23], v[178:181], v[214:217], v[20:23]
	v_mfma_f32_16x16x32_bf16 v[16:19], v[186:189], v[214:217], v[16:19]
	v_mfma_f32_16x16x32_bf16 v[4:7], v[178:181], v[222:225], v[4:7]
	v_mfma_f32_16x16x32_bf16 v[0:3], v[186:189], v[222:225], v[0:3]
	s_setprio 0
	s_barrier
	s_add_i32 s66, 0, 0x18000
	v_add_u32_e32 v158, s66, v149
	s_add_i32 s67, 0, 0x1c000
	ds_read_b128 v[144:147], v158
	ds_read_b128 v[162:165], v158 offset:1024
	ds_read_b128 v[166:169], v158 offset:2048
	ds_read_b128 v[170:173], v158 offset:3072
	v_add_u32_e32 v158, s67, v149
	ds_read_b128 v[174:177], v158
	ds_read_b128 v[178:181], v158 offset:1024
	ds_read_b128 v[182:185], v158 offset:2048
	ds_read_b128 v[186:189], v158 offset:3072
	s_add_u32 s40, s40, 0x40000
	s_addc_u32 s41, s41, 0
	s_mov_b32 m0, s16
	v_lshl_add_u64 v[232:233], s[40:41], 0, v[128:129]
	ds_read_b128 v[190:193], v155 offset:32768
	ds_read_b128 v[198:201], v155 offset:33792
	ds_read_b128 v[202:205], v155 offset:34816
	ds_read_b128 v[206:209], v155 offset:35840
	ds_read_b128 v[210:213], v155 offset:36864
	ds_read_b128 v[214:217], v155 offset:37888
	ds_read_b128 v[218:221], v155 offset:38912
	ds_read_b128 v[222:225], v155 offset:39936
	global_load_lds_dwordx4 v[232:233], off
	v_lshl_add_u64 v[232:233], s[40:41], 0, v[132:133]
	s_mov_b32 m0, s17
	s_nop 0
	global_load_lds_dwordx4 v[232:233], off
	s_waitcnt vmcnt(8)
	s_waitcnt lgkmcnt(0)
	s_barrier
	s_setprio 1
	v_mfma_f32_16x16x32_bf16 v[124:127], v[144:147], v[190:193], v[124:127]
	v_mfma_f32_16x16x32_bf16 v[120:123], v[166:169], v[190:193], v[120:123]
	v_mfma_f32_16x16x32_bf16 v[108:111], v[144:147], v[202:205], v[108:111]
	v_mfma_f32_16x16x32_bf16 v[104:107], v[166:169], v[202:205], v[104:107]
	v_mfma_f32_16x16x32_bf16 v[92:95], v[144:147], v[210:213], v[92:95]
	v_mfma_f32_16x16x32_bf16 v[88:91], v[166:169], v[210:213], v[88:91]
	v_mfma_f32_16x16x32_bf16 v[76:79], v[144:147], v[218:221], v[76:79]
	v_mfma_f32_16x16x32_bf16 v[72:75], v[166:169], v[218:221], v[72:75]
	v_mfma_f32_16x16x32_bf16 v[124:127], v[162:165], v[198:201], v[124:127]
	v_mfma_f32_16x16x32_bf16 v[120:123], v[170:173], v[198:201], v[120:123]
	v_mfma_f32_16x16x32_bf16 v[108:111], v[162:165], v[206:209], v[108:111]
	v_mfma_f32_16x16x32_bf16 v[104:107], v[170:173], v[206:209], v[104:107]
	v_mfma_f32_16x16x32_bf16 v[92:95], v[162:165], v[214:217], v[92:95]
	v_mfma_f32_16x16x32_bf16 v[88:91], v[170:173], v[214:217], v[88:91]
	v_mfma_f32_16x16x32_bf16 v[76:79], v[162:165], v[222:225], v[76:79]
	v_mfma_f32_16x16x32_bf16 v[72:75], v[170:173], v[222:225], v[72:75]
	s_setprio 0
	s_setprio 1
	v_mfma_f32_16x16x32_bf16 v[116:119], v[174:177], v[190:193], v[116:119]
	v_mfma_f32_16x16x32_bf16 v[112:115], v[182:185], v[190:193], v[112:115]
	v_mfma_f32_16x16x32_bf16 v[100:103], v[174:177], v[202:205], v[100:103]
	v_mfma_f32_16x16x32_bf16 v[96:99], v[182:185], v[202:205], v[96:99]
	v_mfma_f32_16x16x32_bf16 v[84:87], v[174:177], v[210:213], v[84:87]
	v_mfma_f32_16x16x32_bf16 v[80:83], v[182:185], v[210:213], v[80:83]
	v_mfma_f32_16x16x32_bf16 v[68:71], v[174:177], v[218:221], v[68:71]
	v_mfma_f32_16x16x32_bf16 v[64:67], v[182:185], v[218:221], v[64:67]
	v_mfma_f32_16x16x32_bf16 v[116:119], v[178:181], v[198:201], v[116:119]
	v_mfma_f32_16x16x32_bf16 v[112:115], v[186:189], v[198:201], v[112:115]
	v_mfma_f32_16x16x32_bf16 v[100:103], v[178:181], v[206:209], v[100:103]
	v_mfma_f32_16x16x32_bf16 v[96:99], v[186:189], v[206:209], v[96:99]
	v_mfma_f32_16x16x32_bf16 v[84:87], v[178:181], v[214:217], v[84:87]
	v_mfma_f32_16x16x32_bf16 v[80:83], v[186:189], v[214:217], v[80:83]
	v_mfma_f32_16x16x32_bf16 v[68:71], v[178:181], v[222:225], v[68:71]
	v_mfma_f32_16x16x32_bf16 v[64:67], v[186:189], v[222:225], v[64:67]
	s_setprio 0
	s_barrier
	s_add_i32 s40, s66, s3
	v_lshl_add_u64 v[156:157], v[156:157], 0, s[12:13]
	s_mov_b32 m0, s40
	ds_read_b128 v[190:193], v155 offset:49152
	ds_read_b128 v[198:201], v155 offset:50176
	ds_read_b128 v[202:205], v155 offset:51200
	ds_read_b128 v[206:209], v155 offset:52224
	ds_read_b128 v[210:213], v155 offset:53248
	ds_read_b128 v[214:217], v155 offset:54272
	ds_read_b128 v[218:221], v155 offset:55296
	ds_read_b128 v[222:225], v155 offset:56320
	global_load_lds_dwordx4 v[156:157], off
	s_add_i32 m0, s40, 0x2000
	s_add_u32 s8, s8, 0x40080
	v_lshl_add_u64 v[156:157], v[226:227], 0, s[12:13]
	s_addc_u32 s9, s9, 0
	s_add_i32 s40, s67, s3
	global_load_lds_dwordx4 v[156:157], off
	v_lshl_add_u64 v[156:157], s[8:9], 0, v[130:131]
	s_mov_b32 m0, s40
	s_nop 0
	global_load_lds_dwordx4 v[156:157], off
	v_lshl_add_u64 v[156:157], s[8:9], 0, v[134:135]
	s_add_i32 m0, s40, 0x2000
	s_nop 0
	global_load_lds_dwordx4 v[156:157], off
	v_lshl_add_u64 v[156:157], v[228:229], 0, s[12:13]
	s_mov_b32 m0, s19
	s_nop 0
	global_load_lds_dwordx4 v[156:157], off
	v_lshl_add_u64 v[156:157], v[230:231], 0, s[12:13]
	s_mov_b32 m0, s33
	s_nop 0
	global_load_lds_dwordx4 v[156:157], off
	s_waitcnt vmcnt(8)
	s_waitcnt lgkmcnt(0)
	s_barrier
	s_setprio 1
	v_mfma_f32_16x16x32_bf16 v[60:63], v[144:147], v[190:193], v[60:63]
	v_mfma_f32_16x16x32_bf16 v[56:59], v[166:169], v[190:193], v[56:59]
	v_mfma_f32_16x16x32_bf16 v[44:47], v[144:147], v[202:205], v[44:47]
	v_mfma_f32_16x16x32_bf16 v[40:43], v[166:169], v[202:205], v[40:43]
	v_mfma_f32_16x16x32_bf16 v[28:31], v[144:147], v[210:213], v[28:31]
	v_mfma_f32_16x16x32_bf16 v[24:27], v[166:169], v[210:213], v[24:27]
	v_mfma_f32_16x16x32_bf16 v[12:15], v[144:147], v[218:221], v[12:15]
	v_mfma_f32_16x16x32_bf16 v[8:11], v[166:169], v[218:221], v[8:11]
	v_mfma_f32_16x16x32_bf16 v[60:63], v[162:165], v[198:201], v[60:63]
	v_mfma_f32_16x16x32_bf16 v[56:59], v[170:173], v[198:201], v[56:59]
	v_mfma_f32_16x16x32_bf16 v[44:47], v[162:165], v[206:209], v[44:47]
	v_mfma_f32_16x16x32_bf16 v[40:43], v[170:173], v[206:209], v[40:43]
	v_mfma_f32_16x16x32_bf16 v[28:31], v[162:165], v[214:217], v[28:31]
	v_mfma_f32_16x16x32_bf16 v[24:27], v[170:173], v[214:217], v[24:27]
	v_mfma_f32_16x16x32_bf16 v[12:15], v[162:165], v[222:225], v[12:15]
	v_mfma_f32_16x16x32_bf16 v[8:11], v[170:173], v[222:225], v[8:11]
	s_setprio 0
	s_setprio 1
	v_mfma_f32_16x16x32_bf16 v[52:55], v[174:177], v[190:193], v[52:55]
	v_mfma_f32_16x16x32_bf16 v[48:51], v[182:185], v[190:193], v[48:51]
	v_mfma_f32_16x16x32_bf16 v[36:39], v[174:177], v[202:205], v[36:39]
	v_mfma_f32_16x16x32_bf16 v[32:35], v[182:185], v[202:205], v[32:35]
	v_mfma_f32_16x16x32_bf16 v[20:23], v[174:177], v[210:213], v[20:23]
	v_mfma_f32_16x16x32_bf16 v[16:19], v[182:185], v[210:213], v[16:19]
	v_mfma_f32_16x16x32_bf16 v[4:7], v[174:177], v[218:221], v[4:7]
	v_mfma_f32_16x16x32_bf16 v[0:3], v[182:185], v[218:221], v[0:3]
	v_mfma_f32_16x16x32_bf16 v[52:55], v[178:181], v[198:201], v[52:55]
	v_mfma_f32_16x16x32_bf16 v[48:51], v[186:189], v[198:201], v[48:51]
	v_mfma_f32_16x16x32_bf16 v[36:39], v[178:181], v[206:209], v[36:39]
	v_mfma_f32_16x16x32_bf16 v[32:35], v[186:189], v[206:209], v[32:35]
	v_mfma_f32_16x16x32_bf16 v[20:23], v[178:181], v[214:217], v[20:23]
	v_mfma_f32_16x16x32_bf16 v[16:19], v[186:189], v[214:217], v[16:19]
	v_mfma_f32_16x16x32_bf16 v[4:7], v[178:181], v[222:225], v[4:7]
	v_mfma_f32_16x16x32_bf16 v[0:3], v[186:189], v[222:225], v[0:3]
	s_setprio 0
	s_barrier
	s_add_i32 s65, s65, 2
	s_add_u32 s38, s38, 0x100
	s_addc_u32 s39, s39, 0
	s_add_u32 s61, s61, 0x100
	s_addc_u32 s64, s64, 0
	s_cmp_gt_u32 s65, 13
	s_cbranch_scc0 .LBB0_666
	s_and_b64 vcc, exec, s[14:15]
	s_cbranch_vccz .LBB0_669
	s_barrier

.LBB0_765:
	ds_read_b128 v[144:147], v154
	ds_read_b128 v[162:165], v154 offset:1024
	ds_read_b128 v[166:169], v154 offset:2048
	ds_read_b128 v[170:173], v154 offset:3072
	ds_read_b128 v[174:177], v155
	ds_read_b128 v[178:181], v155 offset:1024
	ds_read_b128 v[182:185], v155 offset:2048
	ds_read_b128 v[186:189], v155 offset:3072
	s_add_u32 s8, s30, 0xfffc0080
	s_addc_u32 s9, s31, -1
	s_cmp_eq_u32 s60, 12
	s_cselect_b32 s37, s15, s9
	s_cselect_b32 s36, s47, s8
	s_cselect_b32 s9, s13, s59
	s_cselect_b32 s8, s55, s58
	v_lshl_add_u64 v[148:149], s[30:31], 0, v[136:137]
	s_add_i32 m0, s4, 0xc000
	ds_read_b128 v[190:193], v156
	ds_read_b128 v[198:201], v156 offset:1024
	ds_read_b128 v[202:205], v156 offset:2048
	ds_read_b128 v[206:209], v156 offset:3072
	ds_read_b128 v[210:213], v156 offset:4096
	ds_read_b128 v[214:217], v156 offset:5120
	ds_read_b128 v[218:221], v156 offset:6144
	ds_read_b128 v[222:225], v156 offset:7168
	global_load_lds_dwordx4 v[148:149], off
	v_lshl_add_u64 v[148:149], s[30:31], 0, v[138:139]
	s_add_i32 m0, s4, 0xe000
	s_nop 0
	global_load_lds_dwordx4 v[148:149], off
	s_waitcnt vmcnt(8)
	s_waitcnt lgkmcnt(0)
	s_barrier
	s_setprio 1
	v_mfma_f32_16x16x32_bf16 v[124:127], v[144:147], v[190:193], v[124:127]
	v_mfma_f32_16x16x32_bf16 v[120:123], v[166:169], v[190:193], v[120:123]
	v_mfma_f32_16x16x32_bf16 v[108:111], v[144:147], v[202:205], v[108:111]
	v_mfma_f32_16x16x32_bf16 v[104:107], v[166:169], v[202:205], v[104:107]
	v_mfma_f32_16x16x32_bf16 v[92:95], v[144:147], v[210:213], v[92:95]
	v_mfma_f32_16x16x32_bf16 v[88:91], v[166:169], v[210:213], v[88:91]
	v_mfma_f32_16x16x32_bf16 v[76:79], v[144:147], v[218:221], v[76:79]
	v_mfma_f32_16x16x32_bf16 v[72:75], v[166:169], v[218:221], v[72:75]
	v_mfma_f32_16x16x32_bf16 v[124:127], v[162:165], v[198:201], v[124:127]
	v_mfma_f32_16x16x32_bf16 v[120:123], v[170:173], v[198:201], v[120:123]
	v_mfma_f32_16x16x32_bf16 v[108:111], v[162:165], v[206:209], v[108:111]
	v_mfma_f32_16x16x32_bf16 v[104:107], v[170:173], v[206:209], v[104:107]
	v_mfma_f32_16x16x32_bf16 v[92:95], v[162:165], v[214:217], v[92:95]
	v_mfma_f32_16x16x32_bf16 v[88:91], v[170:173], v[214:217], v[88:91]
	v_mfma_f32_16x16x32_bf16 v[76:79], v[162:165], v[222:225], v[76:79]
	v_mfma_f32_16x16x32_bf16 v[72:75], v[170:173], v[222:225], v[72:75]
	s_setprio 0
	s_setprio 1
	v_mfma_f32_16x16x32_bf16 v[116:119], v[174:177], v[190:193], v[116:119]
	v_mfma_f32_16x16x32_bf16 v[112:115], v[182:185], v[190:193], v[112:115]
	v_mfma_f32_16x16x32_bf16 v[100:103], v[174:177], v[202:205], v[100:103]
	v_mfma_f32_16x16x32_bf16 v[96:99], v[182:185], v[202:205], v[96:99]
	v_mfma_f32_16x16x32_bf16 v[84:87], v[174:177], v[210:213], v[84:87]
	v_mfma_f32_16x16x32_bf16 v[80:83], v[182:185], v[210:213], v[80:83]
	v_mfma_f32_16x16x32_bf16 v[68:71], v[174:177], v[218:221], v[68:71]
	v_mfma_f32_16x16x32_bf16 v[64:67], v[182:185], v[218:221], v[64:67]
	v_mfma_f32_16x16x32_bf16 v[116:119], v[178:181], v[198:201], v[116:119]
	v_mfma_f32_16x16x32_bf16 v[112:115], v[186:189], v[198:201], v[112:115]
	v_mfma_f32_16x16x32_bf16 v[100:103], v[178:181], v[206:209], v[100:103]
	v_mfma_f32_16x16x32_bf16 v[96:99], v[186:189], v[206:209], v[96:99]
	v_mfma_f32_16x16x32_bf16 v[84:87], v[178:181], v[214:217], v[84:87]
	v_mfma_f32_16x16x32_bf16 v[80:83], v[186:189], v[214:217], v[80:83]
	v_mfma_f32_16x16x32_bf16 v[68:71], v[178:181], v[222:225], v[68:71]
	v_mfma_f32_16x16x32_bf16 v[64:67], v[186:189], v[222:225], v[64:67]
	s_setprio 0
	s_barrier
	s_add_i32 s61, s38, s3
	v_lshl_add_u64 v[148:149], s[8:9], 0, v[132:133]
	s_mov_b32 m0, s61
	ds_read_b128 v[190:193], v156 offset:16384
	ds_read_b128 v[198:201], v156 offset:17408
	ds_read_b128 v[202:205], v156 offset:18432
	ds_read_b128 v[206:209], v156 offset:19456
	ds_read_b128 v[210:213], v156 offset:20480
	ds_read_b128 v[214:217], v156 offset:21504
	ds_read_b128 v[218:221], v156 offset:22528
	ds_read_b128 v[222:225], v156 offset:23552
	global_load_lds_dwordx4 v[148:149], off
	s_add_i32 m0, s61, 0x2000
	s_add_u32 s64, s8, 0x40000
	v_lshl_add_u64 v[226:227], s[8:9], 0, v[128:129]
	s_addc_u32 s65, s9, 0
	s_add_i32 s61, s39, s3
	global_load_lds_dwordx4 v[226:227], off
	v_lshl_add_u64 v[228:229], s[64:65], 0, v[132:133]
	s_mov_b32 m0, s61
	v_lshl_add_u64 v[230:231], s[36:37], 0, v[130:131]
	global_load_lds_dwordx4 v[228:229], off
	v_lshl_add_u64 v[228:229], s[64:65], 0, v[128:129]
	s_add_i32 m0, s61, 0x2000
	s_nop 0
	global_load_lds_dwordx4 v[228:229], off
	v_lshl_add_u64 v[228:229], s[36:37], 0, v[134:135]
	s_mov_b32 m0, s4
	s_nop 0
	global_load_lds_dwordx4 v[228:229], off
	s_mov_b32 m0, s5
	s_nop 0
	global_load_lds_dwordx4 v[230:231], off
	s_waitcnt vmcnt(8)
	s_waitcnt lgkmcnt(0)
	s_barrier
	s_setprio 1
	v_mfma_f32_16x16x32_bf16 v[60:63], v[144:147], v[190:193], v[60:63]
	v_mfma_f32_16x16x32_bf16 v[56:59], v[166:169], v[190:193], v[56:59]
	v_mfma_f32_16x16x32_bf16 v[44:47], v[144:147], v[202:205], v[44:47]
	v_mfma_f32_16x16x32_bf16 v[40:43], v[166:169], v[202:205], v[40:43]
	v_mfma_f32_16x16x32_bf16 v[28:31], v[144:147], v[210:213], v[28:31]
	v_mfma_f32_16x16x32_bf16 v[24:27], v[166:169], v[210:213], v[24:27]
	v_mfma_f32_16x16x32_bf16 v[12:15], v[144:147], v[218:221], v[12:15]
	v_mfma_f32_16x16x32_bf16 v[8:11], v[166:169], v[218:221], v[8:11]
	v_mfma_f32_16x16x32_bf16 v[60:63], v[162:165], v[198:201], v[60:63]
	v_mfma_f32_16x16x32_bf16 v[56:59], v[170:173], v[198:201], v[56:59]
	v_mfma_f32_16x16x32_bf16 v[44:47], v[162:165], v[206:209], v[44:47]
	v_mfma_f32_16x16x32_bf16 v[40:43], v[170:173], v[206:209], v[40:43]
	v_mfma_f32_16x16x32_bf16 v[28:31], v[162:165], v[214:217], v[28:31]
	v_mfma_f32_16x16x32_bf16 v[24:27], v[170:173], v[214:217], v[24:27]
	v_mfma_f32_16x16x32_bf16 v[12:15], v[162:165], v[222:225], v[12:15]
	v_mfma_f32_16x16x32_bf16 v[8:11], v[170:173], v[222:225], v[8:11]
	s_setprio 0
	s_setprio 1
	v_mfma_f32_16x16x32_bf16 v[52:55], v[174:177], v[190:193], v[52:55]
	v_mfma_f32_16x16x32_bf16 v[48:51], v[182:185], v[190:193], v[48:51]
	v_mfma_f32_16x16x32_bf16 v[36:39], v[174:177], v[202:205], v[36:39]
	v_mfma_f32_16x16x32_bf16 v[32:35], v[182:185], v[202:205], v[32:35]
	v_mfma_f32_16x16x32_bf16 v[20:23], v[174:177], v[210:213], v[20:23]
	v_mfma_f32_16x16x32_bf16 v[16:19], v[182:185], v[210:213], v[16:19]
	v_mfma_f32_16x16x32_bf16 v[4:7], v[174:177], v[218:221], v[4:7]
	v_mfma_f32_16x16x32_bf16 v[0:3], v[182:185], v[218:221], v[0:3]
	v_mfma_f32_16x16x32_bf16 v[52:55], v[178:181], v[198:201], v[52:55]
	v_mfma_f32_16x16x32_bf16 v[48:51], v[186:189], v[198:201], v[48:51]
	v_mfma_f32_16x16x32_bf16 v[36:39], v[178:181], v[206:209], v[36:39]
	v_mfma_f32_16x16x32_bf16 v[32:35], v[186:189], v[206:209], v[32:35]
	v_mfma_f32_16x16x32_bf16 v[20:23], v[178:181], v[214:217], v[20:23]
	v_mfma_f32_16x16x32_bf16 v[16:19], v[186:189], v[214:217], v[16:19]
	v_mfma_f32_16x16x32_bf16 v[4:7], v[178:181], v[222:225], v[4:7]
	v_mfma_f32_16x16x32_bf16 v[0:3], v[186:189], v[222:225], v[0:3]
	s_setprio 0
	s_barrier
	s_add_i32 s61, 0, 0x18000
	v_add_u32_e32 v157, s61, v151
	s_add_i32 s64, 0, 0x1c000
	ds_read_b128 v[144:147], v157
	ds_read_b128 v[162:165], v157 offset:1024
	ds_read_b128 v[166:169], v157 offset:2048
	ds_read_b128 v[170:173], v157 offset:3072
	v_add_u32_e32 v157, s64, v151
	ds_read_b128 v[174:177], v157
	ds_read_b128 v[178:181], v157 offset:1024
	ds_read_b128 v[182:185], v157 offset:2048
	ds_read_b128 v[186:189], v157 offset:3072
	s_add_u32 s36, s36, 0x40000
	s_addc_u32 s37, s37, 0
	s_mov_b32 m0, s16
	v_lshl_add_u64 v[232:233], s[36:37], 0, v[134:135]
	ds_read_b128 v[190:193], v156 offset:32768
	ds_read_b128 v[198:201], v156 offset:33792
	ds_read_b128 v[202:205], v156 offset:34816
	ds_read_b128 v[206:209], v156 offset:35840
	ds_read_b128 v[210:213], v156 offset:36864
	ds_read_b128 v[214:217], v156 offset:37888
	ds_read_b128 v[218:221], v156 offset:38912
	ds_read_b128 v[222:225], v156 offset:39936
	global_load_lds_dwordx4 v[232:233], off
	v_lshl_add_u64 v[232:233], s[36:37], 0, v[130:131]
	s_mov_b32 m0, s17
	s_nop 0
	global_load_lds_dwordx4 v[232:233], off
	s_waitcnt vmcnt(8)
	s_waitcnt lgkmcnt(0)
	s_barrier
	s_setprio 1
	v_mfma_f32_16x16x32_bf16 v[124:127], v[144:147], v[190:193], v[124:127]
	v_mfma_f32_16x16x32_bf16 v[120:123], v[166:169], v[190:193], v[120:123]
	v_mfma_f32_16x16x32_bf16 v[108:111], v[144:147], v[202:205], v[108:111]
	v_mfma_f32_16x16x32_bf16 v[104:107], v[166:169], v[202:205], v[104:107]
	v_mfma_f32_16x16x32_bf16 v[92:95], v[144:147], v[210:213], v[92:95]
	v_mfma_f32_16x16x32_bf16 v[88:91], v[166:169], v[210:213], v[88:91]
	v_mfma_f32_16x16x32_bf16 v[76:79], v[144:147], v[218:221], v[76:79]
	v_mfma_f32_16x16x32_bf16 v[72:75], v[166:169], v[218:221], v[72:75]
	v_mfma_f32_16x16x32_bf16 v[124:127], v[162:165], v[198:201], v[124:127]
	v_mfma_f32_16x16x32_bf16 v[120:123], v[170:173], v[198:201], v[120:123]
	v_mfma_f32_16x16x32_bf16 v[108:111], v[162:165], v[206:209], v[108:111]
	v_mfma_f32_16x16x32_bf16 v[104:107], v[170:173], v[206:209], v[104:107]
	v_mfma_f32_16x16x32_bf16 v[92:95], v[162:165], v[214:217], v[92:95]
	v_mfma_f32_16x16x32_bf16 v[88:91], v[170:173], v[214:217], v[88:91]
	v_mfma_f32_16x16x32_bf16 v[76:79], v[162:165], v[222:225], v[76:79]
	v_mfma_f32_16x16x32_bf16 v[72:75], v[170:173], v[222:225], v[72:75]
	s_setprio 0
	s_setprio 1
	v_mfma_f32_16x16x32_bf16 v[116:119], v[174:177], v[190:193], v[116:119]
	v_mfma_f32_16x16x32_bf16 v[112:115], v[182:185], v[190:193], v[112:115]
	v_mfma_f32_16x16x32_bf16 v[100:103], v[174:177], v[202:205], v[100:103]
	v_mfma_f32_16x16x32_bf16 v[96:99], v[182:185], v[202:205], v[96:99]
	v_mfma_f32_16x16x32_bf16 v[84:87], v[174:177], v[210:213], v[84:87]
	v_mfma_f32_16x16x32_bf16 v[80:83], v[182:185], v[210:213], v[80:83]
	v_mfma_f32_16x16x32_bf16 v[68:71], v[174:177], v[218:221], v[68:71]
	v_mfma_f32_16x16x32_bf16 v[64:67], v[182:185], v[218:221], v[64:67]
	v_mfma_f32_16x16x32_bf16 v[116:119], v[178:181], v[198:201], v[116:119]
	v_mfma_f32_16x16x32_bf16 v[112:115], v[186:189], v[198:201], v[112:115]
	v_mfma_f32_16x16x32_bf16 v[100:103], v[178:181], v[206:209], v[100:103]
	v_mfma_f32_16x16x32_bf16 v[96:99], v[186:189], v[206:209], v[96:99]
	v_mfma_f32_16x16x32_bf16 v[84:87], v[178:181], v[214:217], v[84:87]
	v_mfma_f32_16x16x32_bf16 v[80:83], v[186:189], v[214:217], v[80:83]
	v_mfma_f32_16x16x32_bf16 v[68:71], v[178:181], v[222:225], v[68:71]
	v_mfma_f32_16x16x32_bf16 v[64:67], v[186:189], v[222:225], v[64:67]
	s_setprio 0
	s_barrier
	s_add_i32 s36, s61, s3
	v_lshl_add_u64 v[148:149], v[148:149], 0, s[6:7]
	s_mov_b32 m0, s36
	ds_read_b128 v[190:193], v156 offset:49152
	ds_read_b128 v[198:201], v156 offset:50176
	ds_read_b128 v[202:205], v156 offset:51200
	ds_read_b128 v[206:209], v156 offset:52224
	ds_read_b128 v[210:213], v156 offset:53248
	ds_read_b128 v[214:217], v156 offset:54272
	ds_read_b128 v[218:221], v156 offset:55296
	ds_read_b128 v[222:225], v156 offset:56320
	global_load_lds_dwordx4 v[148:149], off
	s_add_i32 m0, s36, 0x2000
	s_add_u32 s8, s8, 0x40080
	v_lshl_add_u64 v[148:149], v[226:227], 0, s[6:7]
	s_addc_u32 s9, s9, 0
	s_add_i32 s36, s64, s3
	global_load_lds_dwordx4 v[148:149], off
	v_lshl_add_u64 v[148:149], s[8:9], 0, v[132:133]
	s_mov_b32 m0, s36
	s_nop 0
	global_load_lds_dwordx4 v[148:149], off
	v_lshl_add_u64 v[148:149], s[8:9], 0, v[128:129]
	s_add_i32 m0, s36, 0x2000
	s_nop 0
	global_load_lds_dwordx4 v[148:149], off
	v_lshl_add_u64 v[148:149], v[228:229], 0, s[6:7]
	s_mov_b32 m0, s29
	s_nop 0
	global_load_lds_dwordx4 v[148:149], off
	v_lshl_add_u64 v[148:149], v[230:231], 0, s[6:7]
	s_mov_b32 m0, s33
	s_nop 0
	global_load_lds_dwordx4 v[148:149], off
	s_waitcnt vmcnt(8)
	s_waitcnt lgkmcnt(0)
	s_barrier
	s_setprio 1
	v_mfma_f32_16x16x32_bf16 v[60:63], v[144:147], v[190:193], v[60:63]
	v_mfma_f32_16x16x32_bf16 v[56:59], v[166:169], v[190:193], v[56:59]
	v_mfma_f32_16x16x32_bf16 v[44:47], v[144:147], v[202:205], v[44:47]
	v_mfma_f32_16x16x32_bf16 v[40:43], v[166:169], v[202:205], v[40:43]
	v_mfma_f32_16x16x32_bf16 v[28:31], v[144:147], v[210:213], v[28:31]
	v_mfma_f32_16x16x32_bf16 v[24:27], v[166:169], v[210:213], v[24:27]
	v_mfma_f32_16x16x32_bf16 v[12:15], v[144:147], v[218:221], v[12:15]
	v_mfma_f32_16x16x32_bf16 v[8:11], v[166:169], v[218:221], v[8:11]
	v_mfma_f32_16x16x32_bf16 v[60:63], v[162:165], v[198:201], v[60:63]
	v_mfma_f32_16x16x32_bf16 v[56:59], v[170:173], v[198:201], v[56:59]
	v_mfma_f32_16x16x32_bf16 v[44:47], v[162:165], v[206:209], v[44:47]
	v_mfma_f32_16x16x32_bf16 v[40:43], v[170:173], v[206:209], v[40:43]
	v_mfma_f32_16x16x32_bf16 v[28:31], v[162:165], v[214:217], v[28:31]
	v_mfma_f32_16x16x32_bf16 v[24:27], v[170:173], v[214:217], v[24:27]
	v_mfma_f32_16x16x32_bf16 v[12:15], v[162:165], v[222:225], v[12:15]
	v_mfma_f32_16x16x32_bf16 v[8:11], v[170:173], v[222:225], v[8:11]
	s_setprio 0
	s_setprio 1
	v_mfma_f32_16x16x32_bf16 v[52:55], v[174:177], v[190:193], v[52:55]
	v_mfma_f32_16x16x32_bf16 v[48:51], v[182:185], v[190:193], v[48:51]
	v_mfma_f32_16x16x32_bf16 v[36:39], v[174:177], v[202:205], v[36:39]
	v_mfma_f32_16x16x32_bf16 v[32:35], v[182:185], v[202:205], v[32:35]
	v_mfma_f32_16x16x32_bf16 v[20:23], v[174:177], v[210:213], v[20:23]
	v_mfma_f32_16x16x32_bf16 v[16:19], v[182:185], v[210:213], v[16:19]
	v_mfma_f32_16x16x32_bf16 v[4:7], v[174:177], v[218:221], v[4:7]
	v_mfma_f32_16x16x32_bf16 v[0:3], v[182:185], v[218:221], v[0:3]
	v_mfma_f32_16x16x32_bf16 v[52:55], v[178:181], v[198:201], v[52:55]
	v_mfma_f32_16x16x32_bf16 v[48:51], v[186:189], v[198:201], v[48:51]
	v_mfma_f32_16x16x32_bf16 v[36:39], v[178:181], v[206:209], v[36:39]
	v_mfma_f32_16x16x32_bf16 v[32:35], v[186:189], v[206:209], v[32:35]
	v_mfma_f32_16x16x32_bf16 v[20:23], v[178:181], v[214:217], v[20:23]
	v_mfma_f32_16x16x32_bf16 v[16:19], v[186:189], v[214:217], v[16:19]
	v_mfma_f32_16x16x32_bf16 v[4:7], v[178:181], v[222:225], v[4:7]
	v_mfma_f32_16x16x32_bf16 v[0:3], v[186:189], v[222:225], v[0:3]
	s_setprio 0
	s_barrier
	s_add_i32 s60, s60, 2
	s_add_u32 s30, s30, 0x100
	s_addc_u32 s31, s31, 0
	s_add_u32 s58, s58, 0x100
	s_addc_u32 s59, s59, 0
	s_cmp_gt_u32 s60, 13
	s_cbranch_scc0 .LBB0_765
	s_and_b64 vcc, exec, s[10:11]
	s_cbranch_vccz .LBB0_768
	s_barrier

.LBB0_841:
	ds_read_b128 v[144:147], v153
	ds_read_b128 v[162:165], v153 offset:1024
	ds_read_b128 v[166:169], v153 offset:2048
	ds_read_b128 v[170:173], v153 offset:3072
	ds_read_b128 v[174:177], v154
	ds_read_b128 v[178:181], v154 offset:1024
	ds_read_b128 v[182:185], v154 offset:2048
	ds_read_b128 v[186:189], v154 offset:3072
	s_add_u32 s8, s36, 0xfff00080
	s_addc_u32 s9, s37, -1
	s_cmp_eq_u32 s65, 60
	s_cselect_b32 s39, s25, s9
	s_cselect_b32 s38, s31, s8
	s_cselect_b32 s9, s21, s64
	s_cselect_b32 s8, s60, s61
	v_lshl_add_u64 v[156:157], s[36:37], 0, v[136:137]
	s_add_i32 m0, s4, 0xc000
	ds_read_b128 v[190:193], v155
	ds_read_b128 v[198:201], v155 offset:1024
	ds_read_b128 v[202:205], v155 offset:2048
	ds_read_b128 v[206:209], v155 offset:3072
	ds_read_b128 v[210:213], v155 offset:4096
	ds_read_b128 v[214:217], v155 offset:5120
	ds_read_b128 v[218:221], v155 offset:6144
	ds_read_b128 v[222:225], v155 offset:7168
	global_load_lds_dwordx4 v[156:157], off
	v_lshl_add_u64 v[156:157], s[36:37], 0, v[138:139]
	s_add_i32 m0, s4, 0xe000
	s_nop 0
	global_load_lds_dwordx4 v[156:157], off
	s_waitcnt vmcnt(8)
	s_waitcnt lgkmcnt(0)
	s_barrier
	s_setprio 1
	v_mfma_f32_16x16x32_bf16 v[124:127], v[144:147], v[190:193], v[124:127]
	v_mfma_f32_16x16x32_bf16 v[120:123], v[166:169], v[190:193], v[120:123]
	v_mfma_f32_16x16x32_bf16 v[108:111], v[144:147], v[202:205], v[108:111]
	v_mfma_f32_16x16x32_bf16 v[104:107], v[166:169], v[202:205], v[104:107]
	v_mfma_f32_16x16x32_bf16 v[92:95], v[144:147], v[210:213], v[92:95]
	v_mfma_f32_16x16x32_bf16 v[88:91], v[166:169], v[210:213], v[88:91]
	v_mfma_f32_16x16x32_bf16 v[76:79], v[144:147], v[218:221], v[76:79]
	v_mfma_f32_16x16x32_bf16 v[72:75], v[166:169], v[218:221], v[72:75]
	v_mfma_f32_16x16x32_bf16 v[124:127], v[162:165], v[198:201], v[124:127]
	v_mfma_f32_16x16x32_bf16 v[120:123], v[170:173], v[198:201], v[120:123]
	v_mfma_f32_16x16x32_bf16 v[108:111], v[162:165], v[206:209], v[108:111]
	v_mfma_f32_16x16x32_bf16 v[104:107], v[170:173], v[206:209], v[104:107]
	v_mfma_f32_16x16x32_bf16 v[92:95], v[162:165], v[214:217], v[92:95]
	v_mfma_f32_16x16x32_bf16 v[88:91], v[170:173], v[214:217], v[88:91]
	v_mfma_f32_16x16x32_bf16 v[76:79], v[162:165], v[222:225], v[76:79]
	v_mfma_f32_16x16x32_bf16 v[72:75], v[170:173], v[222:225], v[72:75]
	s_setprio 0
	s_setprio 1
	v_mfma_f32_16x16x32_bf16 v[116:119], v[174:177], v[190:193], v[116:119]
	v_mfma_f32_16x16x32_bf16 v[112:115], v[182:185], v[190:193], v[112:115]
	v_mfma_f32_16x16x32_bf16 v[100:103], v[174:177], v[202:205], v[100:103]
	v_mfma_f32_16x16x32_bf16 v[96:99], v[182:185], v[202:205], v[96:99]
	v_mfma_f32_16x16x32_bf16 v[84:87], v[174:177], v[210:213], v[84:87]
	v_mfma_f32_16x16x32_bf16 v[80:83], v[182:185], v[210:213], v[80:83]
	v_mfma_f32_16x16x32_bf16 v[68:71], v[174:177], v[218:221], v[68:71]
	v_mfma_f32_16x16x32_bf16 v[64:67], v[182:185], v[218:221], v[64:67]
	v_mfma_f32_16x16x32_bf16 v[116:119], v[178:181], v[198:201], v[116:119]
	v_mfma_f32_16x16x32_bf16 v[112:115], v[186:189], v[198:201], v[112:115]
	v_mfma_f32_16x16x32_bf16 v[100:103], v[178:181], v[206:209], v[100:103]
	v_mfma_f32_16x16x32_bf16 v[96:99], v[186:189], v[206:209], v[96:99]
	v_mfma_f32_16x16x32_bf16 v[84:87], v[178:181], v[214:217], v[84:87]
	v_mfma_f32_16x16x32_bf16 v[80:83], v[186:189], v[214:217], v[80:83]
	v_mfma_f32_16x16x32_bf16 v[68:71], v[178:181], v[222:225], v[68:71]
	v_mfma_f32_16x16x32_bf16 v[64:67], v[186:189], v[222:225], v[64:67]
	s_setprio 0
	s_barrier
	s_add_i32 s66, s55, s3
	v_lshl_add_u64 v[156:157], s[8:9], 0, v[130:131]
	s_mov_b32 m0, s66
	ds_read_b128 v[190:193], v155 offset:16384
	ds_read_b128 v[198:201], v155 offset:17408
	ds_read_b128 v[202:205], v155 offset:18432
	ds_read_b128 v[206:209], v155 offset:19456
	ds_read_b128 v[210:213], v155 offset:20480
	ds_read_b128 v[214:217], v155 offset:21504
	ds_read_b128 v[218:221], v155 offset:22528
	ds_read_b128 v[222:225], v155 offset:23552
	global_load_lds_dwordx4 v[156:157], off
	s_add_i32 m0, s66, 0x2000
	s_add_u32 s66, s8, 0x100000
	v_lshl_add_u64 v[226:227], s[8:9], 0, v[134:135]
	s_addc_u32 s67, s9, 0
	s_add_i32 s73, s58, s3
	global_load_lds_dwordx4 v[226:227], off
	v_lshl_add_u64 v[228:229], s[66:67], 0, v[130:131]
	s_mov_b32 m0, s73
	v_lshl_add_u64 v[230:231], s[38:39], 0, v[132:133]
	global_load_lds_dwordx4 v[228:229], off
	v_lshl_add_u64 v[228:229], s[66:67], 0, v[134:135]
	s_add_i32 m0, s73, 0x2000
	s_nop 0
	global_load_lds_dwordx4 v[228:229], off
	v_lshl_add_u64 v[228:229], s[38:39], 0, v[128:129]
	s_mov_b32 m0, s4
	s_nop 0
	global_load_lds_dwordx4 v[228:229], off
	s_mov_b32 m0, s5
	s_nop 0
	global_load_lds_dwordx4 v[230:231], off
	s_waitcnt vmcnt(8)
	s_waitcnt lgkmcnt(0)
	s_barrier
	s_setprio 1
	v_mfma_f32_16x16x32_bf16 v[60:63], v[144:147], v[190:193], v[60:63]
	v_mfma_f32_16x16x32_bf16 v[56:59], v[166:169], v[190:193], v[56:59]
	v_mfma_f32_16x16x32_bf16 v[44:47], v[144:147], v[202:205], v[44:47]
	v_mfma_f32_16x16x32_bf16 v[40:43], v[166:169], v[202:205], v[40:43]
	v_mfma_f32_16x16x32_bf16 v[28:31], v[144:147], v[210:213], v[28:31]
	v_mfma_f32_16x16x32_bf16 v[24:27], v[166:169], v[210:213], v[24:27]
	v_mfma_f32_16x16x32_bf16 v[12:15], v[144:147], v[218:221], v[12:15]
	v_mfma_f32_16x16x32_bf16 v[8:11], v[166:169], v[218:221], v[8:11]
	v_mfma_f32_16x16x32_bf16 v[60:63], v[162:165], v[198:201], v[60:63]
	v_mfma_f32_16x16x32_bf16 v[56:59], v[170:173], v[198:201], v[56:59]
	v_mfma_f32_16x16x32_bf16 v[44:47], v[162:165], v[206:209], v[44:47]
	v_mfma_f32_16x16x32_bf16 v[40:43], v[170:173], v[206:209], v[40:43]
	v_mfma_f32_16x16x32_bf16 v[28:31], v[162:165], v[214:217], v[28:31]
	v_mfma_f32_16x16x32_bf16 v[24:27], v[170:173], v[214:217], v[24:27]
	v_mfma_f32_16x16x32_bf16 v[12:15], v[162:165], v[222:225], v[12:15]
	v_mfma_f32_16x16x32_bf16 v[8:11], v[170:173], v[222:225], v[8:11]
	s_setprio 0
	s_setprio 1
	v_mfma_f32_16x16x32_bf16 v[52:55], v[174:177], v[190:193], v[52:55]
	v_mfma_f32_16x16x32_bf16 v[48:51], v[182:185], v[190:193], v[48:51]
	v_mfma_f32_16x16x32_bf16 v[36:39], v[174:177], v[202:205], v[36:39]
	v_mfma_f32_16x16x32_bf16 v[32:35], v[182:185], v[202:205], v[32:35]
	v_mfma_f32_16x16x32_bf16 v[20:23], v[174:177], v[210:213], v[20:23]
	v_mfma_f32_16x16x32_bf16 v[16:19], v[182:185], v[210:213], v[16:19]
	v_mfma_f32_16x16x32_bf16 v[4:7], v[174:177], v[218:221], v[4:7]
	v_mfma_f32_16x16x32_bf16 v[0:3], v[182:185], v[218:221], v[0:3]
	v_mfma_f32_16x16x32_bf16 v[52:55], v[178:181], v[198:201], v[52:55]
	v_mfma_f32_16x16x32_bf16 v[48:51], v[186:189], v[198:201], v[48:51]
	v_mfma_f32_16x16x32_bf16 v[36:39], v[178:181], v[206:209], v[36:39]
	v_mfma_f32_16x16x32_bf16 v[32:35], v[186:189], v[206:209], v[32:35]
	v_mfma_f32_16x16x32_bf16 v[20:23], v[178:181], v[214:217], v[20:23]
	v_mfma_f32_16x16x32_bf16 v[16:19], v[186:189], v[214:217], v[16:19]
	v_mfma_f32_16x16x32_bf16 v[4:7], v[178:181], v[222:225], v[4:7]
	v_mfma_f32_16x16x32_bf16 v[0:3], v[186:189], v[222:225], v[0:3]
	s_setprio 0
	s_barrier
	s_add_i32 s66, 0, 0x18000
	v_add_u32_e32 v158, s66, v149
	s_add_i32 s67, 0, 0x1c000
	ds_read_b128 v[144:147], v158
	ds_read_b128 v[162:165], v158 offset:1024
	ds_read_b128 v[166:169], v158 offset:2048
	ds_read_b128 v[170:173], v158 offset:3072
	v_add_u32_e32 v158, s67, v149
	ds_read_b128 v[174:177], v158
	ds_read_b128 v[178:181], v158 offset:1024
	ds_read_b128 v[182:185], v158 offset:2048
	ds_read_b128 v[186:189], v158 offset:3072
	s_add_u32 s38, s38, 0x100000
	s_addc_u32 s39, s39, 0
	s_mov_b32 m0, s16
	v_lshl_add_u64 v[232:233], s[38:39], 0, v[128:129]
	ds_read_b128 v[190:193], v155 offset:32768
	ds_read_b128 v[198:201], v155 offset:33792
	ds_read_b128 v[202:205], v155 offset:34816
	ds_read_b128 v[206:209], v155 offset:35840
	ds_read_b128 v[210:213], v155 offset:36864
	ds_read_b128 v[214:217], v155 offset:37888
	ds_read_b128 v[218:221], v155 offset:38912
	ds_read_b128 v[222:225], v155 offset:39936
	global_load_lds_dwordx4 v[232:233], off
	v_lshl_add_u64 v[232:233], s[38:39], 0, v[132:133]
	s_mov_b32 m0, s17
	s_nop 0
	global_load_lds_dwordx4 v[232:233], off
	s_waitcnt vmcnt(8)
	s_waitcnt lgkmcnt(0)
	s_barrier
	s_setprio 1
	v_mfma_f32_16x16x32_bf16 v[124:127], v[144:147], v[190:193], v[124:127]
	v_mfma_f32_16x16x32_bf16 v[120:123], v[166:169], v[190:193], v[120:123]
	v_mfma_f32_16x16x32_bf16 v[108:111], v[144:147], v[202:205], v[108:111]
	v_mfma_f32_16x16x32_bf16 v[104:107], v[166:169], v[202:205], v[104:107]
	v_mfma_f32_16x16x32_bf16 v[92:95], v[144:147], v[210:213], v[92:95]
	v_mfma_f32_16x16x32_bf16 v[88:91], v[166:169], v[210:213], v[88:91]
	v_mfma_f32_16x16x32_bf16 v[76:79], v[144:147], v[218:221], v[76:79]
	v_mfma_f32_16x16x32_bf16 v[72:75], v[166:169], v[218:221], v[72:75]
	v_mfma_f32_16x16x32_bf16 v[124:127], v[162:165], v[198:201], v[124:127]
	v_mfma_f32_16x16x32_bf16 v[120:123], v[170:173], v[198:201], v[120:123]
	v_mfma_f32_16x16x32_bf16 v[108:111], v[162:165], v[206:209], v[108:111]
	v_mfma_f32_16x16x32_bf16 v[104:107], v[170:173], v[206:209], v[104:107]
	v_mfma_f32_16x16x32_bf16 v[92:95], v[162:165], v[214:217], v[92:95]
	v_mfma_f32_16x16x32_bf16 v[88:91], v[170:173], v[214:217], v[88:91]
	v_mfma_f32_16x16x32_bf16 v[76:79], v[162:165], v[222:225], v[76:79]
	v_mfma_f32_16x16x32_bf16 v[72:75], v[170:173], v[222:225], v[72:75]
	s_setprio 0
	s_setprio 1
	v_mfma_f32_16x16x32_bf16 v[116:119], v[174:177], v[190:193], v[116:119]
	v_mfma_f32_16x16x32_bf16 v[112:115], v[182:185], v[190:193], v[112:115]
	v_mfma_f32_16x16x32_bf16 v[100:103], v[174:177], v[202:205], v[100:103]
	v_mfma_f32_16x16x32_bf16 v[96:99], v[182:185], v[202:205], v[96:99]
	v_mfma_f32_16x16x32_bf16 v[84:87], v[174:177], v[210:213], v[84:87]
	v_mfma_f32_16x16x32_bf16 v[80:83], v[182:185], v[210:213], v[80:83]
	v_mfma_f32_16x16x32_bf16 v[68:71], v[174:177], v[218:221], v[68:71]
	v_mfma_f32_16x16x32_bf16 v[64:67], v[182:185], v[218:221], v[64:67]
	v_mfma_f32_16x16x32_bf16 v[116:119], v[178:181], v[198:201], v[116:119]
	v_mfma_f32_16x16x32_bf16 v[112:115], v[186:189], v[198:201], v[112:115]
	v_mfma_f32_16x16x32_bf16 v[100:103], v[178:181], v[206:209], v[100:103]
	v_mfma_f32_16x16x32_bf16 v[96:99], v[186:189], v[206:209], v[96:99]
	v_mfma_f32_16x16x32_bf16 v[84:87], v[178:181], v[214:217], v[84:87]
	v_mfma_f32_16x16x32_bf16 v[80:83], v[186:189], v[214:217], v[80:83]
	v_mfma_f32_16x16x32_bf16 v[68:71], v[178:181], v[222:225], v[68:71]
	v_mfma_f32_16x16x32_bf16 v[64:67], v[186:189], v[222:225], v[64:67]
	s_setprio 0
	s_barrier
	s_add_i32 s38, s66, s3
	v_lshl_add_u64 v[156:157], v[156:157], 0, s[12:13]
	s_mov_b32 m0, s38
	ds_read_b128 v[190:193], v155 offset:49152
	ds_read_b128 v[198:201], v155 offset:50176
	ds_read_b128 v[202:205], v155 offset:51200
	ds_read_b128 v[206:209], v155 offset:52224
	ds_read_b128 v[210:213], v155 offset:53248
	ds_read_b128 v[214:217], v155 offset:54272
	ds_read_b128 v[218:221], v155 offset:55296
	ds_read_b128 v[222:225], v155 offset:56320
	global_load_lds_dwordx4 v[156:157], off
	s_add_i32 m0, s38, 0x2000
	s_add_u32 s8, s8, 0x100080
	v_lshl_add_u64 v[156:157], v[226:227], 0, s[12:13]
	s_addc_u32 s9, s9, 0
	s_add_i32 s38, s67, s3
	global_load_lds_dwordx4 v[156:157], off
	v_lshl_add_u64 v[156:157], s[8:9], 0, v[130:131]
	s_mov_b32 m0, s38
	s_nop 0
	global_load_lds_dwordx4 v[156:157], off
	v_lshl_add_u64 v[156:157], s[8:9], 0, v[134:135]
	s_add_i32 m0, s38, 0x2000
	s_nop 0
	global_load_lds_dwordx4 v[156:157], off
	v_lshl_add_u64 v[156:157], v[228:229], 0, s[12:13]
	s_mov_b32 m0, s40
	s_nop 0
	global_load_lds_dwordx4 v[156:157], off
	v_lshl_add_u64 v[156:157], v[230:231], 0, s[12:13]
	s_mov_b32 m0, s41
	s_nop 0
	global_load_lds_dwordx4 v[156:157], off
	s_waitcnt vmcnt(8)
	s_waitcnt lgkmcnt(0)
	s_barrier
	s_setprio 1
	v_mfma_f32_16x16x32_bf16 v[60:63], v[144:147], v[190:193], v[60:63]
	v_mfma_f32_16x16x32_bf16 v[56:59], v[166:169], v[190:193], v[56:59]
	v_mfma_f32_16x16x32_bf16 v[44:47], v[144:147], v[202:205], v[44:47]
	v_mfma_f32_16x16x32_bf16 v[40:43], v[166:169], v[202:205], v[40:43]
	v_mfma_f32_16x16x32_bf16 v[28:31], v[144:147], v[210:213], v[28:31]
	v_mfma_f32_16x16x32_bf16 v[24:27], v[166:169], v[210:213], v[24:27]
	v_mfma_f32_16x16x32_bf16 v[12:15], v[144:147], v[218:221], v[12:15]
	v_mfma_f32_16x16x32_bf16 v[8:11], v[166:169], v[218:221], v[8:11]
	v_mfma_f32_16x16x32_bf16 v[60:63], v[162:165], v[198:201], v[60:63]
	v_mfma_f32_16x16x32_bf16 v[56:59], v[170:173], v[198:201], v[56:59]
	v_mfma_f32_16x16x32_bf16 v[44:47], v[162:165], v[206:209], v[44:47]
	v_mfma_f32_16x16x32_bf16 v[40:43], v[170:173], v[206:209], v[40:43]
	v_mfma_f32_16x16x32_bf16 v[28:31], v[162:165], v[214:217], v[28:31]
	v_mfma_f32_16x16x32_bf16 v[24:27], v[170:173], v[214:217], v[24:27]
	v_mfma_f32_16x16x32_bf16 v[12:15], v[162:165], v[222:225], v[12:15]
	v_mfma_f32_16x16x32_bf16 v[8:11], v[170:173], v[222:225], v[8:11]
	s_setprio 0
	s_setprio 1
	v_mfma_f32_16x16x32_bf16 v[52:55], v[174:177], v[190:193], v[52:55]
	v_mfma_f32_16x16x32_bf16 v[48:51], v[182:185], v[190:193], v[48:51]
	v_mfma_f32_16x16x32_bf16 v[36:39], v[174:177], v[202:205], v[36:39]
	v_mfma_f32_16x16x32_bf16 v[32:35], v[182:185], v[202:205], v[32:35]
	v_mfma_f32_16x16x32_bf16 v[20:23], v[174:177], v[210:213], v[20:23]
	v_mfma_f32_16x16x32_bf16 v[16:19], v[182:185], v[210:213], v[16:19]
	v_mfma_f32_16x16x32_bf16 v[4:7], v[174:177], v[218:221], v[4:7]
	v_mfma_f32_16x16x32_bf16 v[0:3], v[182:185], v[218:221], v[0:3]
	v_mfma_f32_16x16x32_bf16 v[52:55], v[178:181], v[198:201], v[52:55]
	v_mfma_f32_16x16x32_bf16 v[48:51], v[186:189], v[198:201], v[48:51]
	v_mfma_f32_16x16x32_bf16 v[36:39], v[178:181], v[206:209], v[36:39]
	v_mfma_f32_16x16x32_bf16 v[32:35], v[186:189], v[206:209], v[32:35]
	v_mfma_f32_16x16x32_bf16 v[20:23], v[178:181], v[214:217], v[20:23]
	v_mfma_f32_16x16x32_bf16 v[16:19], v[186:189], v[214:217], v[16:19]
	v_mfma_f32_16x16x32_bf16 v[4:7], v[178:181], v[222:225], v[4:7]
	v_mfma_f32_16x16x32_bf16 v[0:3], v[186:189], v[222:225], v[0:3]
	s_setprio 0
	s_barrier
	s_add_i32 s65, s65, 2
	s_add_u32 s36, s36, 0x100
	s_addc_u32 s37, s37, 0
	s_add_u32 s61, s61, 0x100
	s_addc_u32 s64, s64, 0
	s_cmp_gt_u32 s65, 61
	s_cbranch_scc0 .LBB0_841
	s_and_b64 vcc, exec, s[14:15]
	s_cbranch_vccz .LBB0_844
	s_barrier

.LBB0_938:
	ds_read_b128 v[146:149], v169
	ds_read_b128 v[150:153], v169 offset:1024
	ds_read_b128 v[154:157], v169 offset:2048
	ds_read_b128 v[174:177], v169 offset:3072
	ds_read_b128 v[178:181], v170
	ds_read_b128 v[182:185], v170 offset:1024
	ds_read_b128 v[186:189], v170 offset:2048
	ds_read_b128 v[190:193], v170 offset:3072
	s_add_u32 s8, s26, 0xfffc0080
	s_addc_u32 s9, s27, -1
	s_cmp_eq_u32 s61, 12
	s_cselect_b32 s29, s15, s9
	s_cselect_b32 s28, s55, s8
	s_cselect_b32 s9, s13, s60
	s_cselect_b32 s8, s58, s59
	v_lshl_add_u64 v[230:231], s[26:27], 0, v[138:139]
	s_add_i32 m0, s5, 0xc000
	ds_read_b128 v[198:201], v171
	ds_read_b128 v[202:205], v171 offset:1024
	ds_read_b128 v[206:209], v171 offset:2048
	ds_read_b128 v[210:213], v171 offset:3072
	ds_read_b128 v[214:217], v171 offset:4096
	ds_read_b128 v[218:221], v171 offset:5120
	ds_read_b128 v[222:225], v171 offset:6144
	ds_read_b128 v[226:229], v171 offset:7168
	global_load_lds_dwordx4 v[230:231], off
	v_lshl_add_u64 v[230:231], s[26:27], 0, v[140:141]
	s_add_i32 m0, s5, 0xe000
	s_nop 0
	global_load_lds_dwordx4 v[230:231], off
	s_waitcnt vmcnt(8)
	s_waitcnt lgkmcnt(0)
	s_barrier
	s_setprio 1
	v_mfma_f32_16x16x32_bf16 v[124:127], v[146:149], v[198:201], v[124:127]
	v_mfma_f32_16x16x32_bf16 v[120:123], v[154:157], v[198:201], v[120:123]
	v_mfma_f32_16x16x32_bf16 v[116:119], v[146:149], v[206:209], v[116:119]
	v_mfma_f32_16x16x32_bf16 v[108:111], v[154:157], v[206:209], v[108:111]
	v_mfma_f32_16x16x32_bf16 v[100:103], v[146:149], v[214:217], v[100:103]
	v_mfma_f32_16x16x32_bf16 v[92:95], v[154:157], v[214:217], v[92:95]
	v_mfma_f32_16x16x32_bf16 v[84:87], v[146:149], v[222:225], v[84:87]
	v_mfma_f32_16x16x32_bf16 v[76:79], v[154:157], v[222:225], v[76:79]
	v_mfma_f32_16x16x32_bf16 v[124:127], v[150:153], v[202:205], v[124:127]
	v_mfma_f32_16x16x32_bf16 v[120:123], v[174:177], v[202:205], v[120:123]
	v_mfma_f32_16x16x32_bf16 v[116:119], v[150:153], v[210:213], v[116:119]
	v_mfma_f32_16x16x32_bf16 v[108:111], v[174:177], v[210:213], v[108:111]
	v_mfma_f32_16x16x32_bf16 v[100:103], v[150:153], v[218:221], v[100:103]
	v_mfma_f32_16x16x32_bf16 v[92:95], v[174:177], v[218:221], v[92:95]
	v_mfma_f32_16x16x32_bf16 v[84:87], v[150:153], v[226:229], v[84:87]
	v_mfma_f32_16x16x32_bf16 v[76:79], v[174:177], v[226:229], v[76:79]
	s_setprio 0
	s_setprio 1
	v_mfma_f32_16x16x32_bf16 v[112:115], v[178:181], v[198:201], v[112:115]
	v_mfma_f32_16x16x32_bf16 v[104:107], v[186:189], v[198:201], v[104:107]
	v_mfma_f32_16x16x32_bf16 v[96:99], v[178:181], v[206:209], v[96:99]
	v_mfma_f32_16x16x32_bf16 v[88:91], v[186:189], v[206:209], v[88:91]
	v_mfma_f32_16x16x32_bf16 v[80:83], v[178:181], v[214:217], v[80:83]
	v_mfma_f32_16x16x32_bf16 v[72:75], v[186:189], v[214:217], v[72:75]
	v_mfma_f32_16x16x32_bf16 v[68:71], v[178:181], v[222:225], v[68:71]
	v_mfma_f32_16x16x32_bf16 v[64:67], v[186:189], v[222:225], v[64:67]
	v_mfma_f32_16x16x32_bf16 v[112:115], v[182:185], v[202:205], v[112:115]
	v_mfma_f32_16x16x32_bf16 v[104:107], v[190:193], v[202:205], v[104:107]
	v_mfma_f32_16x16x32_bf16 v[96:99], v[182:185], v[210:213], v[96:99]
	v_mfma_f32_16x16x32_bf16 v[88:91], v[190:193], v[210:213], v[88:91]
	v_mfma_f32_16x16x32_bf16 v[80:83], v[182:185], v[218:221], v[80:83]
	v_mfma_f32_16x16x32_bf16 v[72:75], v[190:193], v[218:221], v[72:75]
	v_mfma_f32_16x16x32_bf16 v[68:71], v[182:185], v[226:229], v[68:71]
	v_mfma_f32_16x16x32_bf16 v[64:67], v[190:193], v[226:229], v[64:67]
	s_setprio 0
	s_barrier
	s_add_i32 s62, s37, s3
	v_lshl_add_u64 v[230:231], s[8:9], 0, v[132:133]
	s_mov_b32 m0, s62
	ds_read_b128 v[198:201], v171 offset:16384
	ds_read_b128 v[202:205], v171 offset:17408
	ds_read_b128 v[206:209], v171 offset:18432
	ds_read_b128 v[210:213], v171 offset:19456
	ds_read_b128 v[214:217], v171 offset:20480
	ds_read_b128 v[218:221], v171 offset:21504
	ds_read_b128 v[222:225], v171 offset:22528
	ds_read_b128 v[226:229], v171 offset:23552
	global_load_lds_dwordx4 v[230:231], off
	s_add_i32 m0, s62, 0x2000
	s_add_u32 s62, s8, 0x40000
	v_lshl_add_u64 v[232:233], s[8:9], 0, v[128:129]
	s_addc_u32 s63, s9, 0
	s_add_i32 s64, s38, s3
	global_load_lds_dwordx4 v[232:233], off
	v_lshl_add_u64 v[234:235], s[62:63], 0, v[132:133]
	s_mov_b32 m0, s64
	v_lshl_add_u64 v[236:237], s[28:29], 0, v[130:131]
	global_load_lds_dwordx4 v[234:235], off
	v_lshl_add_u64 v[234:235], s[62:63], 0, v[128:129]
	s_add_i32 m0, s64, 0x2000
	s_nop 0
	global_load_lds_dwordx4 v[234:235], off
	v_lshl_add_u64 v[234:235], s[28:29], 0, v[134:135]
	s_mov_b32 m0, s5
	s_nop 0
	global_load_lds_dwordx4 v[234:235], off
	s_mov_b32 m0, s25
	s_nop 0
	global_load_lds_dwordx4 v[236:237], off
	s_waitcnt vmcnt(8)
	s_waitcnt lgkmcnt(0)
	s_barrier
	s_setprio 1
	v_mfma_f32_16x16x32_bf16 v[60:63], v[146:149], v[198:201], v[60:63]
	v_mfma_f32_16x16x32_bf16 v[56:59], v[154:157], v[198:201], v[56:59]
	v_mfma_f32_16x16x32_bf16 v[52:55], v[146:149], v[206:209], v[52:55]
	v_mfma_f32_16x16x32_bf16 v[44:47], v[154:157], v[206:209], v[44:47]
	v_mfma_f32_16x16x32_bf16 v[32:35], v[146:149], v[214:217], v[32:35]
	v_mfma_f32_16x16x32_bf16 v[24:27], v[154:157], v[214:217], v[24:27]
	v_mfma_f32_16x16x32_bf16 v[20:23], v[146:149], v[222:225], v[20:23]
	v_mfma_f32_16x16x32_bf16 v[12:15], v[154:157], v[222:225], v[12:15]
	v_mfma_f32_16x16x32_bf16 v[60:63], v[150:153], v[202:205], v[60:63]
	v_mfma_f32_16x16x32_bf16 v[56:59], v[174:177], v[202:205], v[56:59]
	v_mfma_f32_16x16x32_bf16 v[52:55], v[150:153], v[210:213], v[52:55]
	v_mfma_f32_16x16x32_bf16 v[44:47], v[174:177], v[210:213], v[44:47]
	v_mfma_f32_16x16x32_bf16 v[32:35], v[150:153], v[218:221], v[32:35]
	v_mfma_f32_16x16x32_bf16 v[24:27], v[174:177], v[218:221], v[24:27]
	v_mfma_f32_16x16x32_bf16 v[20:23], v[150:153], v[226:229], v[20:23]
	v_mfma_f32_16x16x32_bf16 v[12:15], v[174:177], v[226:229], v[12:15]
	s_setprio 0
	s_setprio 1
	v_mfma_f32_16x16x32_bf16 v[48:51], v[178:181], v[198:201], v[48:51]
	v_mfma_f32_16x16x32_bf16 v[40:43], v[186:189], v[198:201], v[40:43]
	v_mfma_f32_16x16x32_bf16 v[36:39], v[178:181], v[206:209], v[36:39]
	v_mfma_f32_16x16x32_bf16 v[28:31], v[186:189], v[206:209], v[28:31]
	v_mfma_f32_16x16x32_bf16 v[16:19], v[178:181], v[214:217], v[16:19]
	v_mfma_f32_16x16x32_bf16 v[8:11], v[186:189], v[214:217], v[8:11]
	v_mfma_f32_16x16x32_bf16 v[4:7], v[178:181], v[222:225], v[4:7]
	v_mfma_f32_16x16x32_bf16 v[0:3], v[186:189], v[222:225], v[0:3]
	v_mfma_f32_16x16x32_bf16 v[48:51], v[182:185], v[202:205], v[48:51]
	v_mfma_f32_16x16x32_bf16 v[40:43], v[190:193], v[202:205], v[40:43]
	v_mfma_f32_16x16x32_bf16 v[36:39], v[182:185], v[210:213], v[36:39]
	v_mfma_f32_16x16x32_bf16 v[28:31], v[190:193], v[210:213], v[28:31]
	v_mfma_f32_16x16x32_bf16 v[16:19], v[182:185], v[218:221], v[16:19]
	v_mfma_f32_16x16x32_bf16 v[8:11], v[190:193], v[218:221], v[8:11]
	v_mfma_f32_16x16x32_bf16 v[4:7], v[182:185], v[226:229], v[4:7]
	v_mfma_f32_16x16x32_bf16 v[0:3], v[190:193], v[226:229], v[0:3]
	s_setprio 0
	s_barrier
	s_add_i32 s62, 0, 0x18000
	s_add_i32 s63, 0, 0x1c000
	v_add_u32_e32 v174, s62, v162
	v_add_u32_e32 v190, s63, v162
	ds_read_b128 v[146:149], v174
	ds_read_b128 v[150:153], v174 offset:1024
	ds_read_b128 v[154:157], v174 offset:2048
	ds_read_b128 v[174:177], v174 offset:3072
	ds_read_b128 v[178:181], v190
	ds_read_b128 v[182:185], v190 offset:1024
	ds_read_b128 v[186:189], v190 offset:2048
	ds_read_b128 v[190:193], v190 offset:3072
	s_add_u32 s28, s28, 0x40000
	s_addc_u32 s29, s29, 0
	s_mov_b32 m0, s30
	v_lshl_add_u64 v[238:239], s[28:29], 0, v[134:135]
	ds_read_b128 v[198:201], v171 offset:32768
	ds_read_b128 v[202:205], v171 offset:33792
	ds_read_b128 v[206:209], v171 offset:34816
	ds_read_b128 v[210:213], v171 offset:35840
	ds_read_b128 v[214:217], v171 offset:36864
	ds_read_b128 v[218:221], v171 offset:37888
	ds_read_b128 v[222:225], v171 offset:38912
	ds_read_b128 v[226:229], v171 offset:39936
	global_load_lds_dwordx4 v[238:239], off
	v_lshl_add_u64 v[238:239], s[28:29], 0, v[130:131]
	s_mov_b32 m0, s31
	s_nop 0
	global_load_lds_dwordx4 v[238:239], off
	s_waitcnt vmcnt(8)
	s_waitcnt lgkmcnt(0)
	s_barrier
	s_setprio 1
	v_mfma_f32_16x16x32_bf16 v[124:127], v[146:149], v[198:201], v[124:127]
	v_mfma_f32_16x16x32_bf16 v[120:123], v[154:157], v[198:201], v[120:123]
	v_mfma_f32_16x16x32_bf16 v[116:119], v[146:149], v[206:209], v[116:119]
	v_mfma_f32_16x16x32_bf16 v[108:111], v[154:157], v[206:209], v[108:111]
	v_mfma_f32_16x16x32_bf16 v[100:103], v[146:149], v[214:217], v[100:103]
	v_mfma_f32_16x16x32_bf16 v[92:95], v[154:157], v[214:217], v[92:95]
	v_mfma_f32_16x16x32_bf16 v[84:87], v[146:149], v[222:225], v[84:87]
	v_mfma_f32_16x16x32_bf16 v[76:79], v[154:157], v[222:225], v[76:79]
	v_mfma_f32_16x16x32_bf16 v[124:127], v[150:153], v[202:205], v[124:127]
	v_mfma_f32_16x16x32_bf16 v[120:123], v[174:177], v[202:205], v[120:123]
	v_mfma_f32_16x16x32_bf16 v[116:119], v[150:153], v[210:213], v[116:119]
	v_mfma_f32_16x16x32_bf16 v[108:111], v[174:177], v[210:213], v[108:111]
	v_mfma_f32_16x16x32_bf16 v[100:103], v[150:153], v[218:221], v[100:103]
	v_mfma_f32_16x16x32_bf16 v[92:95], v[174:177], v[218:221], v[92:95]
	v_mfma_f32_16x16x32_bf16 v[84:87], v[150:153], v[226:229], v[84:87]
	v_mfma_f32_16x16x32_bf16 v[76:79], v[174:177], v[226:229], v[76:79]
	s_setprio 0
	s_setprio 1
	v_mfma_f32_16x16x32_bf16 v[112:115], v[178:181], v[198:201], v[112:115]
	v_mfma_f32_16x16x32_bf16 v[104:107], v[186:189], v[198:201], v[104:107]
	v_mfma_f32_16x16x32_bf16 v[96:99], v[178:181], v[206:209], v[96:99]
	v_mfma_f32_16x16x32_bf16 v[88:91], v[186:189], v[206:209], v[88:91]
	v_mfma_f32_16x16x32_bf16 v[80:83], v[178:181], v[214:217], v[80:83]
	v_mfma_f32_16x16x32_bf16 v[72:75], v[186:189], v[214:217], v[72:75]
	v_mfma_f32_16x16x32_bf16 v[68:71], v[178:181], v[222:225], v[68:71]
	v_mfma_f32_16x16x32_bf16 v[64:67], v[186:189], v[222:225], v[64:67]
	v_mfma_f32_16x16x32_bf16 v[112:115], v[182:185], v[202:205], v[112:115]
	v_mfma_f32_16x16x32_bf16 v[104:107], v[190:193], v[202:205], v[104:107]
	v_mfma_f32_16x16x32_bf16 v[96:99], v[182:185], v[210:213], v[96:99]
	v_mfma_f32_16x16x32_bf16 v[88:91], v[190:193], v[210:213], v[88:91]
	v_mfma_f32_16x16x32_bf16 v[80:83], v[182:185], v[218:221], v[80:83]
	v_mfma_f32_16x16x32_bf16 v[72:75], v[190:193], v[218:221], v[72:75]
	v_mfma_f32_16x16x32_bf16 v[68:71], v[182:185], v[226:229], v[68:71]
	v_mfma_f32_16x16x32_bf16 v[64:67], v[190:193], v[226:229], v[64:67]
	s_setprio 0
	s_barrier
	s_add_i32 s28, s62, s3
	v_lshl_add_u64 v[230:231], v[230:231], 0, s[6:7]
	s_mov_b32 m0, s28
	ds_read_b128 v[198:201], v171 offset:49152
	ds_read_b128 v[202:205], v171 offset:50176
	ds_read_b128 v[206:209], v171 offset:51200
	ds_read_b128 v[210:213], v171 offset:52224
	ds_read_b128 v[214:217], v171 offset:53248
	ds_read_b128 v[218:221], v171 offset:54272
	ds_read_b128 v[222:225], v171 offset:55296
	ds_read_b128 v[226:229], v171 offset:56320
	global_load_lds_dwordx4 v[230:231], off
	s_add_i32 m0, s28, 0x2000
	s_add_u32 s8, s8, 0x40080
	v_lshl_add_u64 v[230:231], v[232:233], 0, s[6:7]
	s_addc_u32 s9, s9, 0
	s_add_i32 s28, s63, s3
	global_load_lds_dwordx4 v[230:231], off
	v_lshl_add_u64 v[230:231], s[8:9], 0, v[132:133]
	s_mov_b32 m0, s28
	s_nop 0
	global_load_lds_dwordx4 v[230:231], off
	v_lshl_add_u64 v[230:231], s[8:9], 0, v[128:129]
	s_add_i32 m0, s28, 0x2000
	s_nop 0
	global_load_lds_dwordx4 v[230:231], off
	v_lshl_add_u64 v[230:231], v[234:235], 0, s[6:7]
	s_mov_b32 m0, s33
	s_nop 0
	global_load_lds_dwordx4 v[230:231], off
	v_lshl_add_u64 v[230:231], v[236:237], 0, s[6:7]
	s_mov_b32 m0, s36
	s_nop 0
	global_load_lds_dwordx4 v[230:231], off
	s_waitcnt vmcnt(8)
	s_waitcnt lgkmcnt(0)
	s_barrier
	s_setprio 1
	v_mfma_f32_16x16x32_bf16 v[60:63], v[146:149], v[198:201], v[60:63]
	v_mfma_f32_16x16x32_bf16 v[56:59], v[154:157], v[198:201], v[56:59]
	v_mfma_f32_16x16x32_bf16 v[52:55], v[146:149], v[206:209], v[52:55]
	v_mfma_f32_16x16x32_bf16 v[44:47], v[154:157], v[206:209], v[44:47]
	v_mfma_f32_16x16x32_bf16 v[32:35], v[146:149], v[214:217], v[32:35]
	v_mfma_f32_16x16x32_bf16 v[24:27], v[154:157], v[214:217], v[24:27]
	v_mfma_f32_16x16x32_bf16 v[20:23], v[146:149], v[222:225], v[20:23]
	v_mfma_f32_16x16x32_bf16 v[12:15], v[154:157], v[222:225], v[12:15]
	v_mfma_f32_16x16x32_bf16 v[60:63], v[150:153], v[202:205], v[60:63]
	v_mfma_f32_16x16x32_bf16 v[56:59], v[174:177], v[202:205], v[56:59]
	v_mfma_f32_16x16x32_bf16 v[52:55], v[150:153], v[210:213], v[52:55]
	v_mfma_f32_16x16x32_bf16 v[44:47], v[174:177], v[210:213], v[44:47]
	v_mfma_f32_16x16x32_bf16 v[32:35], v[150:153], v[218:221], v[32:35]
	v_mfma_f32_16x16x32_bf16 v[24:27], v[174:177], v[218:221], v[24:27]
	v_mfma_f32_16x16x32_bf16 v[20:23], v[150:153], v[226:229], v[20:23]
	v_mfma_f32_16x16x32_bf16 v[12:15], v[174:177], v[226:229], v[12:15]
	s_setprio 0
	s_setprio 1
	v_mfma_f32_16x16x32_bf16 v[48:51], v[178:181], v[198:201], v[48:51]
	v_mfma_f32_16x16x32_bf16 v[40:43], v[186:189], v[198:201], v[40:43]
	v_mfma_f32_16x16x32_bf16 v[36:39], v[178:181], v[206:209], v[36:39]
	v_mfma_f32_16x16x32_bf16 v[28:31], v[186:189], v[206:209], v[28:31]
	v_mfma_f32_16x16x32_bf16 v[16:19], v[178:181], v[214:217], v[16:19]
	v_mfma_f32_16x16x32_bf16 v[8:11], v[186:189], v[214:217], v[8:11]
	v_mfma_f32_16x16x32_bf16 v[4:7], v[178:181], v[222:225], v[4:7]
	v_mfma_f32_16x16x32_bf16 v[0:3], v[186:189], v[222:225], v[0:3]
	v_mfma_f32_16x16x32_bf16 v[48:51], v[182:185], v[202:205], v[48:51]
	v_mfma_f32_16x16x32_bf16 v[40:43], v[190:193], v[202:205], v[40:43]
	v_mfma_f32_16x16x32_bf16 v[36:39], v[182:185], v[210:213], v[36:39]
	v_mfma_f32_16x16x32_bf16 v[28:31], v[190:193], v[210:213], v[28:31]
	v_mfma_f32_16x16x32_bf16 v[16:19], v[182:185], v[218:221], v[16:19]
	v_mfma_f32_16x16x32_bf16 v[8:11], v[190:193], v[218:221], v[8:11]
	v_mfma_f32_16x16x32_bf16 v[4:7], v[182:185], v[226:229], v[4:7]
	v_mfma_f32_16x16x32_bf16 v[0:3], v[190:193], v[226:229], v[0:3]
	s_setprio 0
	s_barrier
	s_add_i32 s61, s61, 2
	s_add_u32 s26, s26, 0x100
	s_addc_u32 s27, s27, 0
	s_add_u32 s59, s59, 0x100
	s_addc_u32 s60, s60, 0
	s_cmp_gt_u32 s61, 13
	s_cbranch_scc0 .LBB0_938
	s_and_b64 vcc, exec, s[10:11]
	s_cbranch_vccz .LBB0_941
	s_barrier

.LBB0_1226:
	ds_read_b128 v[144:147], v151
	ds_read_b128 v[154:157], v151 offset:1024
	ds_read_b128 v[158:161], v151 offset:2048
	ds_read_b128 v[162:165], v151 offset:3072
	ds_read_b128 v[166:169], v152
	ds_read_b128 v[170:173], v152 offset:1024
	ds_read_b128 v[174:177], v152 offset:2048
	ds_read_b128 v[178:181], v152 offset:3072
	s_add_u32 s8, s28, 0xfffc0080
	s_addc_u32 s9, s29, -1
	s_cmp_eq_u32 s58, 12
	s_cselect_b32 s31, s21, s9
	s_cselect_b32 s30, s27, s8
	s_cselect_b32 s9, s17, s57
	s_cselect_b32 s8, s53, s55
	v_lshl_add_u64 v[196:197], s[28:29], 0, v[136:137]
	s_add_i32 m0, s4, 0xc000
	ds_read_b128 v[182:185], v153
	ds_read_b128 v[186:189], v153 offset:1024
	ds_read_b128 v[190:193], v153 offset:2048
	ds_read_b128 v[200:203], v153 offset:3072
	ds_read_b128 v[204:207], v153 offset:4096
	ds_read_b128 v[208:211], v153 offset:5120
	ds_read_b128 v[212:215], v153 offset:6144
	ds_read_b128 v[216:219], v153 offset:7168
	global_load_lds_dwordx4 v[196:197], off
	v_lshl_add_u64 v[196:197], s[28:29], 0, v[138:139]
	s_add_i32 m0, s4, 0xe000
	s_nop 0
	global_load_lds_dwordx4 v[196:197], off
	s_waitcnt vmcnt(8)
	s_waitcnt lgkmcnt(0)
	s_barrier
	s_setprio 1
	v_mfma_f32_16x16x32_bf16 v[124:127], v[144:147], v[182:185], v[124:127]
	v_mfma_f32_16x16x32_bf16 v[120:123], v[158:161], v[182:185], v[120:123]
	v_mfma_f32_16x16x32_bf16 v[108:111], v[144:147], v[190:193], v[108:111]
	v_mfma_f32_16x16x32_bf16 v[104:107], v[158:161], v[190:193], v[104:107]
	v_mfma_f32_16x16x32_bf16 v[92:95], v[144:147], v[204:207], v[92:95]
	v_mfma_f32_16x16x32_bf16 v[88:91], v[158:161], v[204:207], v[88:91]
	v_mfma_f32_16x16x32_bf16 v[76:79], v[144:147], v[212:215], v[76:79]
	v_mfma_f32_16x16x32_bf16 v[72:75], v[158:161], v[212:215], v[72:75]
	v_mfma_f32_16x16x32_bf16 v[124:127], v[154:157], v[186:189], v[124:127]
	v_mfma_f32_16x16x32_bf16 v[120:123], v[162:165], v[186:189], v[120:123]
	v_mfma_f32_16x16x32_bf16 v[108:111], v[154:157], v[200:203], v[108:111]
	v_mfma_f32_16x16x32_bf16 v[104:107], v[162:165], v[200:203], v[104:107]
	v_mfma_f32_16x16x32_bf16 v[92:95], v[154:157], v[208:211], v[92:95]
	v_mfma_f32_16x16x32_bf16 v[88:91], v[162:165], v[208:211], v[88:91]
	v_mfma_f32_16x16x32_bf16 v[76:79], v[154:157], v[216:219], v[76:79]
	v_mfma_f32_16x16x32_bf16 v[72:75], v[162:165], v[216:219], v[72:75]
	s_setprio 0
	s_setprio 1
	v_mfma_f32_16x16x32_bf16 v[116:119], v[166:169], v[182:185], v[116:119]
	v_mfma_f32_16x16x32_bf16 v[112:115], v[174:177], v[182:185], v[112:115]
	v_mfma_f32_16x16x32_bf16 v[100:103], v[166:169], v[190:193], v[100:103]
	v_mfma_f32_16x16x32_bf16 v[96:99], v[174:177], v[190:193], v[96:99]
	v_mfma_f32_16x16x32_bf16 v[84:87], v[166:169], v[204:207], v[84:87]
	v_mfma_f32_16x16x32_bf16 v[80:83], v[174:177], v[204:207], v[80:83]
	v_mfma_f32_16x16x32_bf16 v[68:71], v[166:169], v[212:215], v[68:71]
	v_mfma_f32_16x16x32_bf16 v[64:67], v[174:177], v[212:215], v[64:67]
	v_mfma_f32_16x16x32_bf16 v[116:119], v[170:173], v[186:189], v[116:119]
	v_mfma_f32_16x16x32_bf16 v[112:115], v[178:181], v[186:189], v[112:115]
	v_mfma_f32_16x16x32_bf16 v[100:103], v[170:173], v[200:203], v[100:103]
	v_mfma_f32_16x16x32_bf16 v[96:99], v[178:181], v[200:203], v[96:99]
	v_mfma_f32_16x16x32_bf16 v[84:87], v[170:173], v[208:211], v[84:87]
	v_mfma_f32_16x16x32_bf16 v[80:83], v[178:181], v[208:211], v[80:83]
	v_mfma_f32_16x16x32_bf16 v[68:71], v[170:173], v[216:219], v[68:71]
	v_mfma_f32_16x16x32_bf16 v[64:67], v[178:181], v[216:219], v[64:67]
	s_setprio 0
	s_barrier
	s_add_i32 s59, s40, s3
	v_lshl_add_u64 v[196:197], s[8:9], 0, v[130:131]
	s_mov_b32 m0, s59
	ds_read_b128 v[182:185], v153 offset:16384
	ds_read_b128 v[186:189], v153 offset:17408
	ds_read_b128 v[190:193], v153 offset:18432
	ds_read_b128 v[200:203], v153 offset:19456
	ds_read_b128 v[204:207], v153 offset:20480
	ds_read_b128 v[208:211], v153 offset:21504
	ds_read_b128 v[212:215], v153 offset:22528
	ds_read_b128 v[216:219], v153 offset:23552
	global_load_lds_dwordx4 v[196:197], off
	s_add_i32 m0, s59, 0x2000
	s_add_u32 s60, s8, 0x40000
	v_lshl_add_u64 v[220:221], s[8:9], 0, v[134:135]
	s_addc_u32 s61, s9, 0
	s_add_i32 s59, s41, s3
	global_load_lds_dwordx4 v[220:221], off
	v_lshl_add_u64 v[222:223], s[60:61], 0, v[130:131]
	s_mov_b32 m0, s59
	v_lshl_add_u64 v[224:225], s[30:31], 0, v[132:133]
	global_load_lds_dwordx4 v[222:223], off
	v_lshl_add_u64 v[222:223], s[60:61], 0, v[134:135]
	s_add_i32 m0, s59, 0x2000
	s_nop 0
	global_load_lds_dwordx4 v[222:223], off
	v_lshl_add_u64 v[222:223], s[30:31], 0, v[128:129]
	s_mov_b32 m0, s4
	s_nop 0
	global_load_lds_dwordx4 v[222:223], off
	s_mov_b32 m0, s5
	s_nop 0
	global_load_lds_dwordx4 v[224:225], off
	s_waitcnt vmcnt(8)
	s_waitcnt lgkmcnt(0)
	s_barrier
	s_setprio 1
	v_mfma_f32_16x16x32_bf16 v[60:63], v[144:147], v[182:185], v[60:63]
	v_mfma_f32_16x16x32_bf16 v[56:59], v[158:161], v[182:185], v[56:59]
	v_mfma_f32_16x16x32_bf16 v[44:47], v[144:147], v[190:193], v[44:47]
	v_mfma_f32_16x16x32_bf16 v[40:43], v[158:161], v[190:193], v[40:43]
	v_mfma_f32_16x16x32_bf16 v[28:31], v[144:147], v[204:207], v[28:31]
	v_mfma_f32_16x16x32_bf16 v[24:27], v[158:161], v[204:207], v[24:27]
	v_mfma_f32_16x16x32_bf16 v[12:15], v[144:147], v[212:215], v[12:15]
	v_mfma_f32_16x16x32_bf16 v[8:11], v[158:161], v[212:215], v[8:11]
	v_mfma_f32_16x16x32_bf16 v[60:63], v[154:157], v[186:189], v[60:63]
	v_mfma_f32_16x16x32_bf16 v[56:59], v[162:165], v[186:189], v[56:59]
	v_mfma_f32_16x16x32_bf16 v[44:47], v[154:157], v[200:203], v[44:47]
	v_mfma_f32_16x16x32_bf16 v[40:43], v[162:165], v[200:203], v[40:43]
	v_mfma_f32_16x16x32_bf16 v[28:31], v[154:157], v[208:211], v[28:31]
	v_mfma_f32_16x16x32_bf16 v[24:27], v[162:165], v[208:211], v[24:27]
	v_mfma_f32_16x16x32_bf16 v[12:15], v[154:157], v[216:219], v[12:15]
	v_mfma_f32_16x16x32_bf16 v[8:11], v[162:165], v[216:219], v[8:11]
	s_setprio 0
	s_setprio 1
	v_mfma_f32_16x16x32_bf16 v[52:55], v[166:169], v[182:185], v[52:55]
	v_mfma_f32_16x16x32_bf16 v[48:51], v[174:177], v[182:185], v[48:51]
	v_mfma_f32_16x16x32_bf16 v[36:39], v[166:169], v[190:193], v[36:39]
	v_mfma_f32_16x16x32_bf16 v[32:35], v[174:177], v[190:193], v[32:35]
	v_mfma_f32_16x16x32_bf16 v[20:23], v[166:169], v[204:207], v[20:23]
	v_mfma_f32_16x16x32_bf16 v[16:19], v[174:177], v[204:207], v[16:19]
	v_mfma_f32_16x16x32_bf16 v[4:7], v[166:169], v[212:215], v[4:7]
	v_mfma_f32_16x16x32_bf16 v[0:3], v[174:177], v[212:215], v[0:3]
	v_mfma_f32_16x16x32_bf16 v[52:55], v[170:173], v[186:189], v[52:55]
	v_mfma_f32_16x16x32_bf16 v[48:51], v[178:181], v[186:189], v[48:51]
	v_mfma_f32_16x16x32_bf16 v[36:39], v[170:173], v[200:203], v[36:39]
	v_mfma_f32_16x16x32_bf16 v[32:35], v[178:181], v[200:203], v[32:35]
	v_mfma_f32_16x16x32_bf16 v[20:23], v[170:173], v[208:211], v[20:23]
	v_mfma_f32_16x16x32_bf16 v[16:19], v[178:181], v[208:211], v[16:19]
	v_mfma_f32_16x16x32_bf16 v[4:7], v[170:173], v[216:219], v[4:7]
	v_mfma_f32_16x16x32_bf16 v[0:3], v[178:181], v[216:219], v[0:3]
	s_setprio 0
	s_barrier
	s_add_i32 s59, 0, 0x18000
	s_add_i32 s60, 0, 0x1c000
	v_add_u32_e32 v162, s59, v149
	v_add_u32_e32 v178, s60, v149
	ds_read_b128 v[144:147], v162
	ds_read_b128 v[154:157], v162 offset:1024
	ds_read_b128 v[158:161], v162 offset:2048
	ds_read_b128 v[162:165], v162 offset:3072
	ds_read_b128 v[166:169], v178
	ds_read_b128 v[170:173], v178 offset:1024
	ds_read_b128 v[174:177], v178 offset:2048
	ds_read_b128 v[178:181], v178 offset:3072
	s_add_u32 s30, s30, 0x40000
	s_addc_u32 s31, s31, 0
	s_mov_b32 m0, s33
	v_lshl_add_u64 v[226:227], s[30:31], 0, v[128:129]
	ds_read_b128 v[182:185], v153 offset:32768
	ds_read_b128 v[186:189], v153 offset:33792
	ds_read_b128 v[190:193], v153 offset:34816
	ds_read_b128 v[200:203], v153 offset:35840
	ds_read_b128 v[204:207], v153 offset:36864
	ds_read_b128 v[208:211], v153 offset:37888
	ds_read_b128 v[212:215], v153 offset:38912
	ds_read_b128 v[216:219], v153 offset:39936
	global_load_lds_dwordx4 v[226:227], off
	v_lshl_add_u64 v[226:227], s[30:31], 0, v[132:133]
	s_mov_b32 m0, s36
	s_nop 0
	global_load_lds_dwordx4 v[226:227], off
	s_waitcnt vmcnt(8)
	s_waitcnt lgkmcnt(0)
	s_barrier
	s_setprio 1
	v_mfma_f32_16x16x32_bf16 v[124:127], v[144:147], v[182:185], v[124:127]
	v_mfma_f32_16x16x32_bf16 v[120:123], v[158:161], v[182:185], v[120:123]
	v_mfma_f32_16x16x32_bf16 v[108:111], v[144:147], v[190:193], v[108:111]
	v_mfma_f32_16x16x32_bf16 v[104:107], v[158:161], v[190:193], v[104:107]
	v_mfma_f32_16x16x32_bf16 v[92:95], v[144:147], v[204:207], v[92:95]
	v_mfma_f32_16x16x32_bf16 v[88:91], v[158:161], v[204:207], v[88:91]
	v_mfma_f32_16x16x32_bf16 v[76:79], v[144:147], v[212:215], v[76:79]
	v_mfma_f32_16x16x32_bf16 v[72:75], v[158:161], v[212:215], v[72:75]
	v_mfma_f32_16x16x32_bf16 v[124:127], v[154:157], v[186:189], v[124:127]
	v_mfma_f32_16x16x32_bf16 v[120:123], v[162:165], v[186:189], v[120:123]
	v_mfma_f32_16x16x32_bf16 v[108:111], v[154:157], v[200:203], v[108:111]
	v_mfma_f32_16x16x32_bf16 v[104:107], v[162:165], v[200:203], v[104:107]
	v_mfma_f32_16x16x32_bf16 v[92:95], v[154:157], v[208:211], v[92:95]
	v_mfma_f32_16x16x32_bf16 v[88:91], v[162:165], v[208:211], v[88:91]
	v_mfma_f32_16x16x32_bf16 v[76:79], v[154:157], v[216:219], v[76:79]
	v_mfma_f32_16x16x32_bf16 v[72:75], v[162:165], v[216:219], v[72:75]
	s_setprio 0
	s_setprio 1
	v_mfma_f32_16x16x32_bf16 v[116:119], v[166:169], v[182:185], v[116:119]
	v_mfma_f32_16x16x32_bf16 v[112:115], v[174:177], v[182:185], v[112:115]
	v_mfma_f32_16x16x32_bf16 v[100:103], v[166:169], v[190:193], v[100:103]
	v_mfma_f32_16x16x32_bf16 v[96:99], v[174:177], v[190:193], v[96:99]
	v_mfma_f32_16x16x32_bf16 v[84:87], v[166:169], v[204:207], v[84:87]
	v_mfma_f32_16x16x32_bf16 v[80:83], v[174:177], v[204:207], v[80:83]
	v_mfma_f32_16x16x32_bf16 v[68:71], v[166:169], v[212:215], v[68:71]
	v_mfma_f32_16x16x32_bf16 v[64:67], v[174:177], v[212:215], v[64:67]
	v_mfma_f32_16x16x32_bf16 v[116:119], v[170:173], v[186:189], v[116:119]
	v_mfma_f32_16x16x32_bf16 v[112:115], v[178:181], v[186:189], v[112:115]
	v_mfma_f32_16x16x32_bf16 v[100:103], v[170:173], v[200:203], v[100:103]
	v_mfma_f32_16x16x32_bf16 v[96:99], v[178:181], v[200:203], v[96:99]
	v_mfma_f32_16x16x32_bf16 v[84:87], v[170:173], v[208:211], v[84:87]
	v_mfma_f32_16x16x32_bf16 v[80:83], v[178:181], v[208:211], v[80:83]
	v_mfma_f32_16x16x32_bf16 v[68:71], v[170:173], v[216:219], v[68:71]
	v_mfma_f32_16x16x32_bf16 v[64:67], v[178:181], v[216:219], v[64:67]
	s_setprio 0
	s_barrier
	s_add_i32 s30, s59, s3
	v_lshl_add_u64 v[196:197], v[196:197], 0, s[12:13]
	s_mov_b32 m0, s30
	ds_read_b128 v[182:185], v153 offset:49152
	ds_read_b128 v[186:189], v153 offset:50176
	ds_read_b128 v[190:193], v153 offset:51200
	ds_read_b128 v[200:203], v153 offset:52224
	ds_read_b128 v[204:207], v153 offset:53248
	ds_read_b128 v[208:211], v153 offset:54272
	ds_read_b128 v[212:215], v153 offset:55296
	ds_read_b128 v[216:219], v153 offset:56320
	global_load_lds_dwordx4 v[196:197], off
	s_add_i32 m0, s30, 0x2000
	s_add_u32 s8, s8, 0x40080
	v_lshl_add_u64 v[196:197], v[220:221], 0, s[12:13]
	s_addc_u32 s9, s9, 0
	s_add_i32 s30, s60, s3
	global_load_lds_dwordx4 v[196:197], off
	v_lshl_add_u64 v[196:197], s[8:9], 0, v[130:131]
	s_mov_b32 m0, s30
	s_nop 0
	global_load_lds_dwordx4 v[196:197], off
	v_lshl_add_u64 v[196:197], s[8:9], 0, v[134:135]
	s_add_i32 m0, s30, 0x2000
	s_nop 0
	global_load_lds_dwordx4 v[196:197], off
	v_lshl_add_u64 v[196:197], v[222:223], 0, s[12:13]
	s_mov_b32 m0, s38
	s_nop 0
	global_load_lds_dwordx4 v[196:197], off
	v_lshl_add_u64 v[196:197], v[224:225], 0, s[12:13]
	s_mov_b32 m0, s39
	s_nop 0
	global_load_lds_dwordx4 v[196:197], off
	s_waitcnt vmcnt(8)
	s_waitcnt lgkmcnt(0)
	s_barrier
	s_setprio 1
	v_mfma_f32_16x16x32_bf16 v[60:63], v[144:147], v[182:185], v[60:63]
	v_mfma_f32_16x16x32_bf16 v[56:59], v[158:161], v[182:185], v[56:59]
	v_mfma_f32_16x16x32_bf16 v[44:47], v[144:147], v[190:193], v[44:47]
	v_mfma_f32_16x16x32_bf16 v[40:43], v[158:161], v[190:193], v[40:43]
	v_mfma_f32_16x16x32_bf16 v[28:31], v[144:147], v[204:207], v[28:31]
	v_mfma_f32_16x16x32_bf16 v[24:27], v[158:161], v[204:207], v[24:27]
	v_mfma_f32_16x16x32_bf16 v[12:15], v[144:147], v[212:215], v[12:15]
	v_mfma_f32_16x16x32_bf16 v[8:11], v[158:161], v[212:215], v[8:11]
	v_mfma_f32_16x16x32_bf16 v[60:63], v[154:157], v[186:189], v[60:63]
	v_mfma_f32_16x16x32_bf16 v[56:59], v[162:165], v[186:189], v[56:59]
	v_mfma_f32_16x16x32_bf16 v[44:47], v[154:157], v[200:203], v[44:47]
	v_mfma_f32_16x16x32_bf16 v[40:43], v[162:165], v[200:203], v[40:43]
	v_mfma_f32_16x16x32_bf16 v[28:31], v[154:157], v[208:211], v[28:31]
	v_mfma_f32_16x16x32_bf16 v[24:27], v[162:165], v[208:211], v[24:27]
	v_mfma_f32_16x16x32_bf16 v[12:15], v[154:157], v[216:219], v[12:15]
	v_mfma_f32_16x16x32_bf16 v[8:11], v[162:165], v[216:219], v[8:11]
	s_setprio 0
	s_setprio 1
	v_mfma_f32_16x16x32_bf16 v[52:55], v[166:169], v[182:185], v[52:55]
	v_mfma_f32_16x16x32_bf16 v[48:51], v[174:177], v[182:185], v[48:51]
	v_mfma_f32_16x16x32_bf16 v[36:39], v[166:169], v[190:193], v[36:39]
	v_mfma_f32_16x16x32_bf16 v[32:35], v[174:177], v[190:193], v[32:35]
	v_mfma_f32_16x16x32_bf16 v[20:23], v[166:169], v[204:207], v[20:23]
	v_mfma_f32_16x16x32_bf16 v[16:19], v[174:177], v[204:207], v[16:19]
	v_mfma_f32_16x16x32_bf16 v[4:7], v[166:169], v[212:215], v[4:7]
	v_mfma_f32_16x16x32_bf16 v[0:3], v[174:177], v[212:215], v[0:3]
	v_mfma_f32_16x16x32_bf16 v[52:55], v[170:173], v[186:189], v[52:55]
	v_mfma_f32_16x16x32_bf16 v[48:51], v[178:181], v[186:189], v[48:51]
	v_mfma_f32_16x16x32_bf16 v[36:39], v[170:173], v[200:203], v[36:39]
	v_mfma_f32_16x16x32_bf16 v[32:35], v[178:181], v[200:203], v[32:35]
	v_mfma_f32_16x16x32_bf16 v[20:23], v[170:173], v[208:211], v[20:23]
	v_mfma_f32_16x16x32_bf16 v[16:19], v[178:181], v[208:211], v[16:19]
	v_mfma_f32_16x16x32_bf16 v[4:7], v[170:173], v[216:219], v[4:7]
	v_mfma_f32_16x16x32_bf16 v[0:3], v[178:181], v[216:219], v[0:3]
	s_setprio 0
	s_barrier
	s_add_i32 s58, s58, 2
	s_add_u32 s28, s28, 0x100
	s_addc_u32 s29, s29, 0
	s_add_u32 s55, s55, 0x100
	s_addc_u32 s57, s57, 0
	s_cmp_gt_u32 s58, 13
	s_cbranch_scc0 .LBB0_1226
	s_and_b64 vcc, exec, s[14:15]
	s_cbranch_vccz .LBB0_1229
	s_barrier

.LBB0_1325:
	ds_read_b128 v[144:147], v154
	ds_read_b128 v[158:161], v154 offset:1024
	ds_read_b128 v[162:165], v154 offset:2048
	ds_read_b128 v[166:169], v154 offset:3072
	ds_read_b128 v[170:173], v155
	ds_read_b128 v[174:177], v155 offset:1024
	ds_read_b128 v[178:181], v155 offset:2048
	ds_read_b128 v[182:185], v155 offset:3072
	s_add_u32 s8, s24, 0xfffc0080
	s_addc_u32 s9, s25, -1
	s_cmp_eq_u32 s45, 12
	s_cselect_b32 s27, s15, s9
	s_cselect_b32 s26, s39, s8
	s_cselect_b32 s9, s13, s44
	s_cselect_b32 s8, s40, s41
	v_lshl_add_u64 v[148:149], s[24:25], 0, v[136:137]
	s_add_i32 m0, s4, 0xc000
	ds_read_b128 v[186:189], v156
	ds_read_b128 v[190:193], v156 offset:1024
	ds_read_b128 v[196:199], v156 offset:2048
	ds_read_b128 v[200:203], v156 offset:3072
	ds_read_b128 v[204:207], v156 offset:4096
	ds_read_b128 v[208:211], v156 offset:5120
	ds_read_b128 v[212:215], v156 offset:6144
	ds_read_b128 v[216:219], v156 offset:7168
	global_load_lds_dwordx4 v[148:149], off
	v_lshl_add_u64 v[148:149], s[24:25], 0, v[138:139]
	s_add_i32 m0, s4, 0xe000
	s_nop 0
	global_load_lds_dwordx4 v[148:149], off
	s_waitcnt vmcnt(8)
	s_waitcnt lgkmcnt(0)
	s_barrier
	s_setprio 1
	v_mfma_f32_16x16x32_bf16 v[124:127], v[144:147], v[186:189], v[124:127]
	v_mfma_f32_16x16x32_bf16 v[120:123], v[162:165], v[186:189], v[120:123]
	v_mfma_f32_16x16x32_bf16 v[108:111], v[144:147], v[196:199], v[108:111]
	v_mfma_f32_16x16x32_bf16 v[104:107], v[162:165], v[196:199], v[104:107]
	v_mfma_f32_16x16x32_bf16 v[92:95], v[144:147], v[204:207], v[92:95]
	v_mfma_f32_16x16x32_bf16 v[88:91], v[162:165], v[204:207], v[88:91]
	v_mfma_f32_16x16x32_bf16 v[76:79], v[144:147], v[212:215], v[76:79]
	v_mfma_f32_16x16x32_bf16 v[72:75], v[162:165], v[212:215], v[72:75]
	v_mfma_f32_16x16x32_bf16 v[124:127], v[158:161], v[190:193], v[124:127]
	v_mfma_f32_16x16x32_bf16 v[120:123], v[166:169], v[190:193], v[120:123]
	v_mfma_f32_16x16x32_bf16 v[108:111], v[158:161], v[200:203], v[108:111]
	v_mfma_f32_16x16x32_bf16 v[104:107], v[166:169], v[200:203], v[104:107]
	v_mfma_f32_16x16x32_bf16 v[92:95], v[158:161], v[208:211], v[92:95]
	v_mfma_f32_16x16x32_bf16 v[88:91], v[166:169], v[208:211], v[88:91]
	v_mfma_f32_16x16x32_bf16 v[76:79], v[158:161], v[216:219], v[76:79]
	v_mfma_f32_16x16x32_bf16 v[72:75], v[166:169], v[216:219], v[72:75]
	s_setprio 0
	s_setprio 1
	v_mfma_f32_16x16x32_bf16 v[116:119], v[170:173], v[186:189], v[116:119]
	v_mfma_f32_16x16x32_bf16 v[112:115], v[178:181], v[186:189], v[112:115]
	v_mfma_f32_16x16x32_bf16 v[100:103], v[170:173], v[196:199], v[100:103]
	v_mfma_f32_16x16x32_bf16 v[96:99], v[178:181], v[196:199], v[96:99]
	v_mfma_f32_16x16x32_bf16 v[84:87], v[170:173], v[204:207], v[84:87]
	v_mfma_f32_16x16x32_bf16 v[80:83], v[178:181], v[204:207], v[80:83]
	v_mfma_f32_16x16x32_bf16 v[68:71], v[170:173], v[212:215], v[68:71]
	v_mfma_f32_16x16x32_bf16 v[64:67], v[178:181], v[212:215], v[64:67]
	v_mfma_f32_16x16x32_bf16 v[116:119], v[174:177], v[190:193], v[116:119]
	v_mfma_f32_16x16x32_bf16 v[112:115], v[182:185], v[190:193], v[112:115]
	v_mfma_f32_16x16x32_bf16 v[100:103], v[174:177], v[200:203], v[100:103]
	v_mfma_f32_16x16x32_bf16 v[96:99], v[182:185], v[200:203], v[96:99]
	v_mfma_f32_16x16x32_bf16 v[84:87], v[174:177], v[208:211], v[84:87]
	v_mfma_f32_16x16x32_bf16 v[80:83], v[182:185], v[208:211], v[80:83]
	v_mfma_f32_16x16x32_bf16 v[68:71], v[174:177], v[216:219], v[68:71]
	v_mfma_f32_16x16x32_bf16 v[64:67], v[182:185], v[216:219], v[64:67]
	s_setprio 0
	s_barrier
	s_add_i32 s46, s31, s3
	v_lshl_add_u64 v[148:149], s[8:9], 0, v[132:133]
	s_mov_b32 m0, s46
	ds_read_b128 v[186:189], v156 offset:16384
	ds_read_b128 v[190:193], v156 offset:17408
	ds_read_b128 v[196:199], v156 offset:18432
	ds_read_b128 v[200:203], v156 offset:19456
	ds_read_b128 v[204:207], v156 offset:20480
	ds_read_b128 v[208:211], v156 offset:21504
	ds_read_b128 v[212:215], v156 offset:22528
	ds_read_b128 v[216:219], v156 offset:23552
	global_load_lds_dwordx4 v[148:149], off
	s_add_i32 m0, s46, 0x2000
	s_add_u32 s46, s8, 0x40000
	v_lshl_add_u64 v[220:221], s[8:9], 0, v[128:129]
	s_addc_u32 s47, s9, 0
	s_add_i32 s50, s33, s3
	global_load_lds_dwordx4 v[220:221], off
	v_lshl_add_u64 v[222:223], s[46:47], 0, v[132:133]
	s_mov_b32 m0, s50
	v_lshl_add_u64 v[224:225], s[26:27], 0, v[130:131]
	global_load_lds_dwordx4 v[222:223], off
	v_lshl_add_u64 v[222:223], s[46:47], 0, v[128:129]
	s_add_i32 m0, s50, 0x2000
	s_nop 0
	global_load_lds_dwordx4 v[222:223], off
	v_lshl_add_u64 v[222:223], s[26:27], 0, v[134:135]
	s_mov_b32 m0, s4
	s_nop 0
	global_load_lds_dwordx4 v[222:223], off
	s_mov_b32 m0, s5
	s_nop 0
	global_load_lds_dwordx4 v[224:225], off
	s_waitcnt vmcnt(8)
	s_waitcnt lgkmcnt(0)
	s_barrier
	s_setprio 1
	v_mfma_f32_16x16x32_bf16 v[60:63], v[144:147], v[186:189], v[60:63]
	v_mfma_f32_16x16x32_bf16 v[56:59], v[162:165], v[186:189], v[56:59]
	v_mfma_f32_16x16x32_bf16 v[44:47], v[144:147], v[196:199], v[44:47]
	v_mfma_f32_16x16x32_bf16 v[40:43], v[162:165], v[196:199], v[40:43]
	v_mfma_f32_16x16x32_bf16 v[28:31], v[144:147], v[204:207], v[28:31]
	v_mfma_f32_16x16x32_bf16 v[24:27], v[162:165], v[204:207], v[24:27]
	v_mfma_f32_16x16x32_bf16 v[12:15], v[144:147], v[212:215], v[12:15]
	v_mfma_f32_16x16x32_bf16 v[8:11], v[162:165], v[212:215], v[8:11]
	v_mfma_f32_16x16x32_bf16 v[60:63], v[158:161], v[190:193], v[60:63]
	v_mfma_f32_16x16x32_bf16 v[56:59], v[166:169], v[190:193], v[56:59]
	v_mfma_f32_16x16x32_bf16 v[44:47], v[158:161], v[200:203], v[44:47]
	v_mfma_f32_16x16x32_bf16 v[40:43], v[166:169], v[200:203], v[40:43]
	v_mfma_f32_16x16x32_bf16 v[28:31], v[158:161], v[208:211], v[28:31]
	v_mfma_f32_16x16x32_bf16 v[24:27], v[166:169], v[208:211], v[24:27]
	v_mfma_f32_16x16x32_bf16 v[12:15], v[158:161], v[216:219], v[12:15]
	v_mfma_f32_16x16x32_bf16 v[8:11], v[166:169], v[216:219], v[8:11]
	s_setprio 0
	s_setprio 1
	v_mfma_f32_16x16x32_bf16 v[52:55], v[170:173], v[186:189], v[52:55]
	v_mfma_f32_16x16x32_bf16 v[48:51], v[178:181], v[186:189], v[48:51]
	v_mfma_f32_16x16x32_bf16 v[36:39], v[170:173], v[196:199], v[36:39]
	v_mfma_f32_16x16x32_bf16 v[32:35], v[178:181], v[196:199], v[32:35]
	v_mfma_f32_16x16x32_bf16 v[20:23], v[170:173], v[204:207], v[20:23]
	v_mfma_f32_16x16x32_bf16 v[16:19], v[178:181], v[204:207], v[16:19]
	v_mfma_f32_16x16x32_bf16 v[4:7], v[170:173], v[212:215], v[4:7]
	v_mfma_f32_16x16x32_bf16 v[0:3], v[178:181], v[212:215], v[0:3]
	v_mfma_f32_16x16x32_bf16 v[52:55], v[174:177], v[190:193], v[52:55]
	v_mfma_f32_16x16x32_bf16 v[48:51], v[182:185], v[190:193], v[48:51]
	v_mfma_f32_16x16x32_bf16 v[36:39], v[174:177], v[200:203], v[36:39]
	v_mfma_f32_16x16x32_bf16 v[32:35], v[182:185], v[200:203], v[32:35]
	v_mfma_f32_16x16x32_bf16 v[20:23], v[174:177], v[208:211], v[20:23]
	v_mfma_f32_16x16x32_bf16 v[16:19], v[182:185], v[208:211], v[16:19]
	v_mfma_f32_16x16x32_bf16 v[4:7], v[174:177], v[216:219], v[4:7]
	v_mfma_f32_16x16x32_bf16 v[0:3], v[182:185], v[216:219], v[0:3]
	s_setprio 0
	s_barrier
	s_add_i32 s46, 0, 0x18000
	v_add_u32_e32 v157, s46, v151
	s_add_i32 s47, 0, 0x1c000
	ds_read_b128 v[144:147], v157
	ds_read_b128 v[158:161], v157 offset:1024
	ds_read_b128 v[162:165], v157 offset:2048
	ds_read_b128 v[166:169], v157 offset:3072
	v_add_u32_e32 v157, s47, v151
	ds_read_b128 v[170:173], v157
	ds_read_b128 v[174:177], v157 offset:1024
	ds_read_b128 v[178:181], v157 offset:2048
	ds_read_b128 v[182:185], v157 offset:3072
	s_add_u32 s26, s26, 0x40000
	s_addc_u32 s27, s27, 0
	s_mov_b32 m0, s23
	v_lshl_add_u64 v[226:227], s[26:27], 0, v[134:135]
	ds_read_b128 v[186:189], v156 offset:32768
	ds_read_b128 v[190:193], v156 offset:33792
	ds_read_b128 v[196:199], v156 offset:34816
	ds_read_b128 v[200:203], v156 offset:35840
	ds_read_b128 v[204:207], v156 offset:36864
	ds_read_b128 v[208:211], v156 offset:37888
	ds_read_b128 v[212:215], v156 offset:38912
	ds_read_b128 v[216:219], v156 offset:39936
	global_load_lds_dwordx4 v[226:227], off
	v_lshl_add_u64 v[226:227], s[26:27], 0, v[130:131]
	s_mov_b32 m0, s28
	s_nop 0
	global_load_lds_dwordx4 v[226:227], off
	s_waitcnt vmcnt(8)
	s_waitcnt lgkmcnt(0)
	s_barrier
	s_setprio 1
	v_mfma_f32_16x16x32_bf16 v[124:127], v[144:147], v[186:189], v[124:127]
	v_mfma_f32_16x16x32_bf16 v[120:123], v[162:165], v[186:189], v[120:123]
	v_mfma_f32_16x16x32_bf16 v[108:111], v[144:147], v[196:199], v[108:111]
	v_mfma_f32_16x16x32_bf16 v[104:107], v[162:165], v[196:199], v[104:107]
	v_mfma_f32_16x16x32_bf16 v[92:95], v[144:147], v[204:207], v[92:95]
	v_mfma_f32_16x16x32_bf16 v[88:91], v[162:165], v[204:207], v[88:91]
	v_mfma_f32_16x16x32_bf16 v[76:79], v[144:147], v[212:215], v[76:79]
	v_mfma_f32_16x16x32_bf16 v[72:75], v[162:165], v[212:215], v[72:75]
	v_mfma_f32_16x16x32_bf16 v[124:127], v[158:161], v[190:193], v[124:127]
	v_mfma_f32_16x16x32_bf16 v[120:123], v[166:169], v[190:193], v[120:123]
	v_mfma_f32_16x16x32_bf16 v[108:111], v[158:161], v[200:203], v[108:111]
	v_mfma_f32_16x16x32_bf16 v[104:107], v[166:169], v[200:203], v[104:107]
	v_mfma_f32_16x16x32_bf16 v[92:95], v[158:161], v[208:211], v[92:95]
	v_mfma_f32_16x16x32_bf16 v[88:91], v[166:169], v[208:211], v[88:91]
	v_mfma_f32_16x16x32_bf16 v[76:79], v[158:161], v[216:219], v[76:79]
	v_mfma_f32_16x16x32_bf16 v[72:75], v[166:169], v[216:219], v[72:75]
	s_setprio 0
	s_setprio 1
	v_mfma_f32_16x16x32_bf16 v[116:119], v[170:173], v[186:189], v[116:119]
	v_mfma_f32_16x16x32_bf16 v[112:115], v[178:181], v[186:189], v[112:115]
	v_mfma_f32_16x16x32_bf16 v[100:103], v[170:173], v[196:199], v[100:103]
	v_mfma_f32_16x16x32_bf16 v[96:99], v[178:181], v[196:199], v[96:99]
	v_mfma_f32_16x16x32_bf16 v[84:87], v[170:173], v[204:207], v[84:87]
	v_mfma_f32_16x16x32_bf16 v[80:83], v[178:181], v[204:207], v[80:83]
	v_mfma_f32_16x16x32_bf16 v[68:71], v[170:173], v[212:215], v[68:71]
	v_mfma_f32_16x16x32_bf16 v[64:67], v[178:181], v[212:215], v[64:67]
	v_mfma_f32_16x16x32_bf16 v[116:119], v[174:177], v[190:193], v[116:119]
	v_mfma_f32_16x16x32_bf16 v[112:115], v[182:185], v[190:193], v[112:115]
	v_mfma_f32_16x16x32_bf16 v[100:103], v[174:177], v[200:203], v[100:103]
	v_mfma_f32_16x16x32_bf16 v[96:99], v[182:185], v[200:203], v[96:99]
	v_mfma_f32_16x16x32_bf16 v[84:87], v[174:177], v[208:211], v[84:87]
	v_mfma_f32_16x16x32_bf16 v[80:83], v[182:185], v[208:211], v[80:83]
	v_mfma_f32_16x16x32_bf16 v[68:71], v[174:177], v[216:219], v[68:71]
	v_mfma_f32_16x16x32_bf16 v[64:67], v[182:185], v[216:219], v[64:67]
	s_setprio 0
	s_barrier
	s_add_i32 s26, s46, s3
	v_lshl_add_u64 v[148:149], v[148:149], 0, s[6:7]
	s_mov_b32 m0, s26
	ds_read_b128 v[186:189], v156 offset:49152
	ds_read_b128 v[190:193], v156 offset:50176
	ds_read_b128 v[196:199], v156 offset:51200
	ds_read_b128 v[200:203], v156 offset:52224
	ds_read_b128 v[204:207], v156 offset:53248
	ds_read_b128 v[208:211], v156 offset:54272
	ds_read_b128 v[212:215], v156 offset:55296
	ds_read_b128 v[216:219], v156 offset:56320
	global_load_lds_dwordx4 v[148:149], off
	s_add_i32 m0, s26, 0x2000
	s_add_u32 s8, s8, 0x40080
	v_lshl_add_u64 v[148:149], v[220:221], 0, s[6:7]
	s_addc_u32 s9, s9, 0
	s_add_i32 s26, s47, s3
	global_load_lds_dwordx4 v[148:149], off
	v_lshl_add_u64 v[148:149], s[8:9], 0, v[132:133]
	s_mov_b32 m0, s26
	s_nop 0
	global_load_lds_dwordx4 v[148:149], off
	v_lshl_add_u64 v[148:149], s[8:9], 0, v[128:129]
	s_add_i32 m0, s26, 0x2000
	s_nop 0
	global_load_lds_dwordx4 v[148:149], off
	v_lshl_add_u64 v[148:149], v[222:223], 0, s[6:7]
	s_mov_b32 m0, s29
	s_nop 0
	global_load_lds_dwordx4 v[148:149], off
	v_lshl_add_u64 v[148:149], v[224:225], 0, s[6:7]
	s_mov_b32 m0, s30
	s_nop 0
	global_load_lds_dwordx4 v[148:149], off
	s_waitcnt vmcnt(8)
	s_waitcnt lgkmcnt(0)
	s_barrier
	s_setprio 1
	v_mfma_f32_16x16x32_bf16 v[60:63], v[144:147], v[186:189], v[60:63]
	v_mfma_f32_16x16x32_bf16 v[56:59], v[162:165], v[186:189], v[56:59]
	v_mfma_f32_16x16x32_bf16 v[44:47], v[144:147], v[196:199], v[44:47]
	v_mfma_f32_16x16x32_bf16 v[40:43], v[162:165], v[196:199], v[40:43]
	v_mfma_f32_16x16x32_bf16 v[28:31], v[144:147], v[204:207], v[28:31]
	v_mfma_f32_16x16x32_bf16 v[24:27], v[162:165], v[204:207], v[24:27]
	v_mfma_f32_16x16x32_bf16 v[12:15], v[144:147], v[212:215], v[12:15]
	v_mfma_f32_16x16x32_bf16 v[8:11], v[162:165], v[212:215], v[8:11]
	v_mfma_f32_16x16x32_bf16 v[60:63], v[158:161], v[190:193], v[60:63]
	v_mfma_f32_16x16x32_bf16 v[56:59], v[166:169], v[190:193], v[56:59]
	v_mfma_f32_16x16x32_bf16 v[44:47], v[158:161], v[200:203], v[44:47]
	v_mfma_f32_16x16x32_bf16 v[40:43], v[166:169], v[200:203], v[40:43]
	v_mfma_f32_16x16x32_bf16 v[28:31], v[158:161], v[208:211], v[28:31]
	v_mfma_f32_16x16x32_bf16 v[24:27], v[166:169], v[208:211], v[24:27]
	v_mfma_f32_16x16x32_bf16 v[12:15], v[158:161], v[216:219], v[12:15]
	v_mfma_f32_16x16x32_bf16 v[8:11], v[166:169], v[216:219], v[8:11]
	s_setprio 0
	s_setprio 1
	v_mfma_f32_16x16x32_bf16 v[52:55], v[170:173], v[186:189], v[52:55]
	v_mfma_f32_16x16x32_bf16 v[48:51], v[178:181], v[186:189], v[48:51]
	v_mfma_f32_16x16x32_bf16 v[36:39], v[170:173], v[196:199], v[36:39]
	v_mfma_f32_16x16x32_bf16 v[32:35], v[178:181], v[196:199], v[32:35]
	v_mfma_f32_16x16x32_bf16 v[20:23], v[170:173], v[204:207], v[20:23]
	v_mfma_f32_16x16x32_bf16 v[16:19], v[178:181], v[204:207], v[16:19]
	v_mfma_f32_16x16x32_bf16 v[4:7], v[170:173], v[212:215], v[4:7]
	v_mfma_f32_16x16x32_bf16 v[0:3], v[178:181], v[212:215], v[0:3]
	v_mfma_f32_16x16x32_bf16 v[52:55], v[174:177], v[190:193], v[52:55]
	v_mfma_f32_16x16x32_bf16 v[48:51], v[182:185], v[190:193], v[48:51]
	v_mfma_f32_16x16x32_bf16 v[36:39], v[174:177], v[200:203], v[36:39]
	v_mfma_f32_16x16x32_bf16 v[32:35], v[182:185], v[200:203], v[32:35]
	v_mfma_f32_16x16x32_bf16 v[20:23], v[174:177], v[208:211], v[20:23]
	v_mfma_f32_16x16x32_bf16 v[16:19], v[182:185], v[208:211], v[16:19]
	v_mfma_f32_16x16x32_bf16 v[4:7], v[174:177], v[216:219], v[4:7]
	v_mfma_f32_16x16x32_bf16 v[0:3], v[182:185], v[216:219], v[0:3]
	s_setprio 0
	s_barrier
	s_add_i32 s45, s45, 2
	s_add_u32 s24, s24, 0x100
	s_addc_u32 s25, s25, 0
	s_add_u32 s41, s41, 0x100
	s_addc_u32 s44, s44, 0
	s_cmp_gt_u32 s45, 13
	s_cbranch_scc0 .LBB0_1325
	s_and_b64 vcc, exec, s[10:11]
	s_cbranch_vccz .LBB0_1328
	s_barrier

.LBB0_1399:
	ds_read_b128 v[144:147], v153
	ds_read_b128 v[156:159], v153 offset:1024
	ds_read_b128 v[160:163], v153 offset:2048
	ds_read_b128 v[164:167], v153 offset:3072
	ds_read_b128 v[168:171], v154
	ds_read_b128 v[172:175], v154 offset:1024
	ds_read_b128 v[176:179], v154 offset:2048
	ds_read_b128 v[180:183], v154 offset:3072
	s_add_u32 s36, s34, 0xfff00080
	s_addc_u32 s37, s35, -1
	s_cmp_eq_u32 s50, 60
	s_cselect_b32 s39, s25, s37
	s_cselect_b32 s38, s46, s36
	s_cselect_b32 s37, s23, s49
	s_cselect_b32 s36, s47, s48
	v_lshl_add_u64 v[148:149], s[34:35], 0, v[136:137]
	s_add_i32 m0, s4, 0xc000
	ds_read_b128 v[184:187], v155
	ds_read_b128 v[188:191], v155 offset:1024
	ds_read_b128 v[192:195], v155 offset:2048
	ds_read_b128 v[196:199], v155 offset:3072
	ds_read_b128 v[200:203], v155 offset:4096
	ds_read_b128 v[204:207], v155 offset:5120
	ds_read_b128 v[208:211], v155 offset:6144
	ds_read_b128 v[212:215], v155 offset:7168
	global_load_lds_dwordx4 v[148:149], off
	v_lshl_add_u64 v[148:149], s[34:35], 0, v[138:139]
	s_add_i32 m0, s4, 0xe000
	s_nop 0
	global_load_lds_dwordx4 v[148:149], off
	s_waitcnt vmcnt(8)
	s_waitcnt lgkmcnt(0)
	s_barrier
	s_setprio 1
	v_mfma_f32_16x16x32_bf16 v[124:127], v[144:147], v[184:187], v[124:127]
	v_mfma_f32_16x16x32_bf16 v[120:123], v[160:163], v[184:187], v[120:123]
	v_mfma_f32_16x16x32_bf16 v[108:111], v[144:147], v[192:195], v[108:111]
	v_mfma_f32_16x16x32_bf16 v[104:107], v[160:163], v[192:195], v[104:107]
	v_mfma_f32_16x16x32_bf16 v[92:95], v[144:147], v[200:203], v[92:95]
	v_mfma_f32_16x16x32_bf16 v[88:91], v[160:163], v[200:203], v[88:91]
	v_mfma_f32_16x16x32_bf16 v[76:79], v[144:147], v[208:211], v[76:79]
	v_mfma_f32_16x16x32_bf16 v[72:75], v[160:163], v[208:211], v[72:75]
	v_mfma_f32_16x16x32_bf16 v[124:127], v[156:159], v[188:191], v[124:127]
	v_mfma_f32_16x16x32_bf16 v[120:123], v[164:167], v[188:191], v[120:123]
	v_mfma_f32_16x16x32_bf16 v[108:111], v[156:159], v[196:199], v[108:111]
	v_mfma_f32_16x16x32_bf16 v[104:107], v[164:167], v[196:199], v[104:107]
	v_mfma_f32_16x16x32_bf16 v[92:95], v[156:159], v[204:207], v[92:95]
	v_mfma_f32_16x16x32_bf16 v[88:91], v[164:167], v[204:207], v[88:91]
	v_mfma_f32_16x16x32_bf16 v[76:79], v[156:159], v[212:215], v[76:79]
	v_mfma_f32_16x16x32_bf16 v[72:75], v[164:167], v[212:215], v[72:75]
	s_setprio 0
	s_setprio 1
	v_mfma_f32_16x16x32_bf16 v[116:119], v[168:171], v[184:187], v[116:119]
	v_mfma_f32_16x16x32_bf16 v[112:115], v[176:179], v[184:187], v[112:115]
	v_mfma_f32_16x16x32_bf16 v[100:103], v[168:171], v[192:195], v[100:103]
	v_mfma_f32_16x16x32_bf16 v[96:99], v[176:179], v[192:195], v[96:99]
	v_mfma_f32_16x16x32_bf16 v[84:87], v[168:171], v[200:203], v[84:87]
	v_mfma_f32_16x16x32_bf16 v[80:83], v[176:179], v[200:203], v[80:83]
	v_mfma_f32_16x16x32_bf16 v[68:71], v[168:171], v[208:211], v[68:71]
	v_mfma_f32_16x16x32_bf16 v[64:67], v[176:179], v[208:211], v[64:67]
	v_mfma_f32_16x16x32_bf16 v[116:119], v[172:175], v[188:191], v[116:119]
	v_mfma_f32_16x16x32_bf16 v[112:115], v[180:183], v[188:191], v[112:115]
	v_mfma_f32_16x16x32_bf16 v[100:103], v[172:175], v[196:199], v[100:103]
	v_mfma_f32_16x16x32_bf16 v[96:99], v[180:183], v[196:199], v[96:99]
	v_mfma_f32_16x16x32_bf16 v[84:87], v[172:175], v[204:207], v[84:87]
	v_mfma_f32_16x16x32_bf16 v[80:83], v[180:183], v[204:207], v[80:83]
	v_mfma_f32_16x16x32_bf16 v[68:71], v[172:175], v[212:215], v[68:71]
	v_mfma_f32_16x16x32_bf16 v[64:67], v[180:183], v[212:215], v[64:67]
	s_setprio 0
	s_barrier
	s_add_i32 s51, s43, s3
	v_lshl_add_u64 v[148:149], s[36:37], 0, v[132:133]
	s_mov_b32 m0, s51
	ds_read_b128 v[184:187], v155 offset:16384
	ds_read_b128 v[188:191], v155 offset:17408
	ds_read_b128 v[192:195], v155 offset:18432
	ds_read_b128 v[196:199], v155 offset:19456
	ds_read_b128 v[200:203], v155 offset:20480
	ds_read_b128 v[204:207], v155 offset:21504
	ds_read_b128 v[208:211], v155 offset:22528
	ds_read_b128 v[212:215], v155 offset:23552
	global_load_lds_dwordx4 v[148:149], off
	s_add_i32 m0, s51, 0x2000
	s_add_u32 s52, s36, 0x100000
	v_lshl_add_u64 v[216:217], s[36:37], 0, v[128:129]
	s_addc_u32 s53, s37, 0
	s_add_i32 s51, s44, s3
	global_load_lds_dwordx4 v[216:217], off
	v_lshl_add_u64 v[218:219], s[52:53], 0, v[132:133]
	s_mov_b32 m0, s51
	v_lshl_add_u64 v[220:221], s[38:39], 0, v[130:131]
	global_load_lds_dwordx4 v[218:219], off
	v_lshl_add_u64 v[218:219], s[52:53], 0, v[128:129]
	s_add_i32 m0, s51, 0x2000
	s_nop 0
	global_load_lds_dwordx4 v[218:219], off
	v_lshl_add_u64 v[218:219], s[38:39], 0, v[134:135]
	s_mov_b32 m0, s4
	s_nop 0
	global_load_lds_dwordx4 v[218:219], off
	s_mov_b32 m0, s5
	s_nop 0
	global_load_lds_dwordx4 v[220:221], off
	s_waitcnt vmcnt(8)
	s_waitcnt lgkmcnt(0)
	s_barrier
	s_setprio 1
	v_mfma_f32_16x16x32_bf16 v[60:63], v[144:147], v[184:187], v[60:63]
	v_mfma_f32_16x16x32_bf16 v[56:59], v[160:163], v[184:187], v[56:59]
	v_mfma_f32_16x16x32_bf16 v[44:47], v[144:147], v[192:195], v[44:47]
	v_mfma_f32_16x16x32_bf16 v[40:43], v[160:163], v[192:195], v[40:43]
	v_mfma_f32_16x16x32_bf16 v[28:31], v[144:147], v[200:203], v[28:31]
	v_mfma_f32_16x16x32_bf16 v[24:27], v[160:163], v[200:203], v[24:27]
	v_mfma_f32_16x16x32_bf16 v[12:15], v[144:147], v[208:211], v[12:15]
	v_mfma_f32_16x16x32_bf16 v[8:11], v[160:163], v[208:211], v[8:11]
	v_mfma_f32_16x16x32_bf16 v[60:63], v[156:159], v[188:191], v[60:63]
	v_mfma_f32_16x16x32_bf16 v[56:59], v[164:167], v[188:191], v[56:59]
	v_mfma_f32_16x16x32_bf16 v[44:47], v[156:159], v[196:199], v[44:47]
	v_mfma_f32_16x16x32_bf16 v[40:43], v[164:167], v[196:199], v[40:43]
	v_mfma_f32_16x16x32_bf16 v[28:31], v[156:159], v[204:207], v[28:31]
	v_mfma_f32_16x16x32_bf16 v[24:27], v[164:167], v[204:207], v[24:27]
	v_mfma_f32_16x16x32_bf16 v[12:15], v[156:159], v[212:215], v[12:15]
	v_mfma_f32_16x16x32_bf16 v[8:11], v[164:167], v[212:215], v[8:11]
	s_setprio 0
	s_setprio 1
	v_mfma_f32_16x16x32_bf16 v[52:55], v[168:171], v[184:187], v[52:55]
	v_mfma_f32_16x16x32_bf16 v[48:51], v[176:179], v[184:187], v[48:51]
	v_mfma_f32_16x16x32_bf16 v[36:39], v[168:171], v[192:195], v[36:39]
	v_mfma_f32_16x16x32_bf16 v[32:35], v[176:179], v[192:195], v[32:35]
	v_mfma_f32_16x16x32_bf16 v[20:23], v[168:171], v[200:203], v[20:23]
	v_mfma_f32_16x16x32_bf16 v[16:19], v[176:179], v[200:203], v[16:19]
	v_mfma_f32_16x16x32_bf16 v[4:7], v[168:171], v[208:211], v[4:7]
	v_mfma_f32_16x16x32_bf16 v[0:3], v[176:179], v[208:211], v[0:3]
	v_mfma_f32_16x16x32_bf16 v[52:55], v[172:175], v[188:191], v[52:55]
	v_mfma_f32_16x16x32_bf16 v[48:51], v[180:183], v[188:191], v[48:51]
	v_mfma_f32_16x16x32_bf16 v[36:39], v[172:175], v[196:199], v[36:39]
	v_mfma_f32_16x16x32_bf16 v[32:35], v[180:183], v[196:199], v[32:35]
	v_mfma_f32_16x16x32_bf16 v[20:23], v[172:175], v[204:207], v[20:23]
	v_mfma_f32_16x16x32_bf16 v[16:19], v[180:183], v[204:207], v[16:19]
	v_mfma_f32_16x16x32_bf16 v[4:7], v[172:175], v[212:215], v[4:7]
	v_mfma_f32_16x16x32_bf16 v[0:3], v[180:183], v[212:215], v[0:3]
	s_setprio 0
	s_barrier
	s_add_i32 s51, 0, 0x18000
	s_add_i32 s52, 0, 0x1c000
	v_add_u32_e32 v164, s51, v151
	v_add_u32_e32 v180, s52, v151
	ds_read_b128 v[144:147], v164
	ds_read_b128 v[156:159], v164 offset:1024
	ds_read_b128 v[160:163], v164 offset:2048
	ds_read_b128 v[164:167], v164 offset:3072
	ds_read_b128 v[168:171], v180
	ds_read_b128 v[172:175], v180 offset:1024
	ds_read_b128 v[176:179], v180 offset:2048
	ds_read_b128 v[180:183], v180 offset:3072
	s_add_u32 s38, s38, 0x100000
	s_addc_u32 s39, s39, 0
	s_mov_b32 m0, s31
	v_lshl_add_u64 v[222:223], s[38:39], 0, v[134:135]
	ds_read_b128 v[184:187], v155 offset:32768
	ds_read_b128 v[188:191], v155 offset:33792
	ds_read_b128 v[192:195], v155 offset:34816
	ds_read_b128 v[196:199], v155 offset:35840
	ds_read_b128 v[200:203], v155 offset:36864
	ds_read_b128 v[204:207], v155 offset:37888
	ds_read_b128 v[208:211], v155 offset:38912
	ds_read_b128 v[212:215], v155 offset:39936
	global_load_lds_dwordx4 v[222:223], off
	v_lshl_add_u64 v[222:223], s[38:39], 0, v[130:131]
	s_mov_b32 m0, s33
	s_nop 0
	global_load_lds_dwordx4 v[222:223], off
	s_waitcnt vmcnt(8)
	s_waitcnt lgkmcnt(0)
	s_barrier
	s_setprio 1
	v_mfma_f32_16x16x32_bf16 v[124:127], v[144:147], v[184:187], v[124:127]
	v_mfma_f32_16x16x32_bf16 v[120:123], v[160:163], v[184:187], v[120:123]
	v_mfma_f32_16x16x32_bf16 v[108:111], v[144:147], v[192:195], v[108:111]
	v_mfma_f32_16x16x32_bf16 v[104:107], v[160:163], v[192:195], v[104:107]
	v_mfma_f32_16x16x32_bf16 v[92:95], v[144:147], v[200:203], v[92:95]
	v_mfma_f32_16x16x32_bf16 v[88:91], v[160:163], v[200:203], v[88:91]
	v_mfma_f32_16x16x32_bf16 v[76:79], v[144:147], v[208:211], v[76:79]
	v_mfma_f32_16x16x32_bf16 v[72:75], v[160:163], v[208:211], v[72:75]
	v_mfma_f32_16x16x32_bf16 v[124:127], v[156:159], v[188:191], v[124:127]
	v_mfma_f32_16x16x32_bf16 v[120:123], v[164:167], v[188:191], v[120:123]
	v_mfma_f32_16x16x32_bf16 v[108:111], v[156:159], v[196:199], v[108:111]
	v_mfma_f32_16x16x32_bf16 v[104:107], v[164:167], v[196:199], v[104:107]
	v_mfma_f32_16x16x32_bf16 v[92:95], v[156:159], v[204:207], v[92:95]
	v_mfma_f32_16x16x32_bf16 v[88:91], v[164:167], v[204:207], v[88:91]
	v_mfma_f32_16x16x32_bf16 v[76:79], v[156:159], v[212:215], v[76:79]
	v_mfma_f32_16x16x32_bf16 v[72:75], v[164:167], v[212:215], v[72:75]
	s_setprio 0
	s_setprio 1
	v_mfma_f32_16x16x32_bf16 v[116:119], v[168:171], v[184:187], v[116:119]
	v_mfma_f32_16x16x32_bf16 v[112:115], v[176:179], v[184:187], v[112:115]
	v_mfma_f32_16x16x32_bf16 v[100:103], v[168:171], v[192:195], v[100:103]
	v_mfma_f32_16x16x32_bf16 v[96:99], v[176:179], v[192:195], v[96:99]
	v_mfma_f32_16x16x32_bf16 v[84:87], v[168:171], v[200:203], v[84:87]
	v_mfma_f32_16x16x32_bf16 v[80:83], v[176:179], v[200:203], v[80:83]
	v_mfma_f32_16x16x32_bf16 v[68:71], v[168:171], v[208:211], v[68:71]
	v_mfma_f32_16x16x32_bf16 v[64:67], v[176:179], v[208:211], v[64:67]
	v_mfma_f32_16x16x32_bf16 v[116:119], v[172:175], v[188:191], v[116:119]
	v_mfma_f32_16x16x32_bf16 v[112:115], v[180:183], v[188:191], v[112:115]
	v_mfma_f32_16x16x32_bf16 v[100:103], v[172:175], v[196:199], v[100:103]
	v_mfma_f32_16x16x32_bf16 v[96:99], v[180:183], v[196:199], v[96:99]
	v_mfma_f32_16x16x32_bf16 v[84:87], v[172:175], v[204:207], v[84:87]
	v_mfma_f32_16x16x32_bf16 v[80:83], v[180:183], v[204:207], v[80:83]
	v_mfma_f32_16x16x32_bf16 v[68:71], v[172:175], v[212:215], v[68:71]
	v_mfma_f32_16x16x32_bf16 v[64:67], v[180:183], v[212:215], v[64:67]
	s_setprio 0
	s_barrier
	s_add_i32 s38, s51, s3
	v_lshl_add_u64 v[148:149], v[148:149], 0, s[8:9]
	s_mov_b32 m0, s38
	ds_read_b128 v[184:187], v155 offset:49152
	ds_read_b128 v[188:191], v155 offset:50176
	ds_read_b128 v[192:195], v155 offset:51200
	ds_read_b128 v[196:199], v155 offset:52224
	ds_read_b128 v[200:203], v155 offset:53248
	ds_read_b128 v[204:207], v155 offset:54272
	ds_read_b128 v[208:211], v155 offset:55296
	ds_read_b128 v[212:215], v155 offset:56320
	global_load_lds_dwordx4 v[148:149], off
	s_add_i32 m0, s38, 0x2000
	s_add_u32 s36, s36, 0x100080
	v_lshl_add_u64 v[148:149], v[216:217], 0, s[8:9]
	s_addc_u32 s37, s37, 0
	s_add_i32 s38, s52, s3
	global_load_lds_dwordx4 v[148:149], off
	v_lshl_add_u64 v[148:149], s[36:37], 0, v[132:133]
	s_mov_b32 m0, s38
	s_nop 0
	global_load_lds_dwordx4 v[148:149], off
	v_lshl_add_u64 v[148:149], s[36:37], 0, v[128:129]
	s_add_i32 m0, s38, 0x2000
	s_nop 0
	global_load_lds_dwordx4 v[148:149], off
	v_lshl_add_u64 v[148:149], v[218:219], 0, s[8:9]
	s_mov_b32 m0, s41
	s_nop 0
	global_load_lds_dwordx4 v[148:149], off
	v_lshl_add_u64 v[148:149], v[220:221], 0, s[8:9]
	s_mov_b32 m0, s42
	s_nop 0
	global_load_lds_dwordx4 v[148:149], off
	s_waitcnt vmcnt(8)
	s_waitcnt lgkmcnt(0)
	s_barrier
	s_setprio 1
	v_mfma_f32_16x16x32_bf16 v[60:63], v[144:147], v[184:187], v[60:63]
	v_mfma_f32_16x16x32_bf16 v[56:59], v[160:163], v[184:187], v[56:59]
	v_mfma_f32_16x16x32_bf16 v[44:47], v[144:147], v[192:195], v[44:47]
	v_mfma_f32_16x16x32_bf16 v[40:43], v[160:163], v[192:195], v[40:43]
	v_mfma_f32_16x16x32_bf16 v[28:31], v[144:147], v[200:203], v[28:31]
	v_mfma_f32_16x16x32_bf16 v[24:27], v[160:163], v[200:203], v[24:27]
	v_mfma_f32_16x16x32_bf16 v[12:15], v[144:147], v[208:211], v[12:15]
	v_mfma_f32_16x16x32_bf16 v[8:11], v[160:163], v[208:211], v[8:11]
	v_mfma_f32_16x16x32_bf16 v[60:63], v[156:159], v[188:191], v[60:63]
	v_mfma_f32_16x16x32_bf16 v[56:59], v[164:167], v[188:191], v[56:59]
	v_mfma_f32_16x16x32_bf16 v[44:47], v[156:159], v[196:199], v[44:47]
	v_mfma_f32_16x16x32_bf16 v[40:43], v[164:167], v[196:199], v[40:43]
	v_mfma_f32_16x16x32_bf16 v[28:31], v[156:159], v[204:207], v[28:31]
	v_mfma_f32_16x16x32_bf16 v[24:27], v[164:167], v[204:207], v[24:27]
	v_mfma_f32_16x16x32_bf16 v[12:15], v[156:159], v[212:215], v[12:15]
	v_mfma_f32_16x16x32_bf16 v[8:11], v[164:167], v[212:215], v[8:11]
	s_setprio 0
	s_setprio 1
	v_mfma_f32_16x16x32_bf16 v[52:55], v[168:171], v[184:187], v[52:55]
	v_mfma_f32_16x16x32_bf16 v[48:51], v[176:179], v[184:187], v[48:51]
	v_mfma_f32_16x16x32_bf16 v[36:39], v[168:171], v[192:195], v[36:39]
	v_mfma_f32_16x16x32_bf16 v[32:35], v[176:179], v[192:195], v[32:35]
	v_mfma_f32_16x16x32_bf16 v[20:23], v[168:171], v[200:203], v[20:23]
	v_mfma_f32_16x16x32_bf16 v[16:19], v[176:179], v[200:203], v[16:19]
	v_mfma_f32_16x16x32_bf16 v[4:7], v[168:171], v[208:211], v[4:7]
	v_mfma_f32_16x16x32_bf16 v[0:3], v[176:179], v[208:211], v[0:3]
	v_mfma_f32_16x16x32_bf16 v[52:55], v[172:175], v[188:191], v[52:55]
	v_mfma_f32_16x16x32_bf16 v[48:51], v[180:183], v[188:191], v[48:51]
	v_mfma_f32_16x16x32_bf16 v[36:39], v[172:175], v[196:199], v[36:39]
	v_mfma_f32_16x16x32_bf16 v[32:35], v[180:183], v[196:199], v[32:35]
	v_mfma_f32_16x16x32_bf16 v[20:23], v[172:175], v[204:207], v[20:23]
	v_mfma_f32_16x16x32_bf16 v[16:19], v[180:183], v[204:207], v[16:19]
	v_mfma_f32_16x16x32_bf16 v[4:7], v[172:175], v[212:215], v[4:7]
	v_mfma_f32_16x16x32_bf16 v[0:3], v[180:183], v[212:215], v[0:3]
	s_setprio 0
	s_barrier
	s_add_i32 s50, s50, 2
	s_add_u32 s34, s34, 0x100
	s_addc_u32 s35, s35, 0
	s_add_u32 s48, s48, 0x100
	s_addc_u32 s49, s49, 0
	s_cmp_gt_u32 s50, 61
	s_cbranch_scc0 .LBB0_1399
	s_and_b64 vcc, exec, s[10:11]
	s_cbranch_vccz .LBB0_1402
	s_barrier
